# GEMM K-loops: the compiler's second s_waitcnt lgkmcnt(0) right after each compute-segment barrier (counter already zero) deleted, 4 per trip x 7 GEMMs
# speedup vs baseline: 1.0056x; 1.0056x over previous
.LBB0_236:
	ds_read_b128 v[154:157], v150
	ds_read_b128 v[158:161], v150 offset:1024
	ds_read_b128 v[162:165], v150 offset:2048
	ds_read_b128 v[166:169], v150 offset:3072
	ds_read_b128 v[172:175], v151
	ds_read_b128 v[176:179], v151 offset:1024
	ds_read_b128 v[180:183], v151 offset:2048
	ds_read_b128 v[184:187], v151 offset:3072
	s_add_u32 s36, s34, 0xfffc0080
	s_addc_u32 s37, s35, -1
	s_cmp_eq_u32 s66, 12
	s_cselect_b32 s39, s21, s37
	s_cselect_b32 s38, s62, s36
	s_cselect_b32 s37, s19, s65
	s_cselect_b32 s36, s63, s64
	v_lshl_add_u64 v[220:221], s[34:35], 0, v[138:139]
	s_add_i32 m0, s27, 0xc000
	ds_read_b128 v[188:191], v152
	ds_read_b128 v[192:195], v152 offset:1024
	ds_read_b128 v[196:199], v152 offset:2048
	ds_read_b128 v[200:203], v152 offset:3072
	ds_read_b128 v[204:207], v152 offset:4096
	ds_read_b128 v[208:211], v152 offset:5120
	ds_read_b128 v[212:215], v152 offset:6144
	ds_read_b128 v[216:219], v152 offset:7168
	global_load_lds_dwordx4 v[220:221], off
	v_lshl_add_u64 v[220:221], s[34:35], 0, v[140:141]
	s_add_i32 m0, s27, 0xe000
	s_nop 0
	global_load_lds_dwordx4 v[220:221], off
	s_waitcnt vmcnt(8)
	s_waitcnt lgkmcnt(0)
	s_barrier
	s_setprio 1
	v_mfma_f32_16x16x32_bf16 v[124:127], v[154:157], v[188:191], v[124:127]
	v_mfma_f32_16x16x32_bf16 v[120:123], v[162:165], v[188:191], v[120:123]
	v_mfma_f32_16x16x32_bf16 v[116:119], v[154:157], v[196:199], v[116:119]
	v_mfma_f32_16x16x32_bf16 v[112:115], v[162:165], v[196:199], v[112:115]
	v_mfma_f32_16x16x32_bf16 v[108:111], v[154:157], v[204:207], v[108:111]
	v_mfma_f32_16x16x32_bf16 v[100:103], v[162:165], v[204:207], v[100:103]
	v_mfma_f32_16x16x32_bf16 v[76:79], v[154:157], v[212:215], v[76:79]
	v_mfma_f32_16x16x32_bf16 v[72:75], v[162:165], v[212:215], v[72:75]
	v_mfma_f32_16x16x32_bf16 v[124:127], v[158:161], v[192:195], v[124:127]
	v_mfma_f32_16x16x32_bf16 v[120:123], v[166:169], v[192:195], v[120:123]
	v_mfma_f32_16x16x32_bf16 v[116:119], v[158:161], v[200:203], v[116:119]
	v_mfma_f32_16x16x32_bf16 v[112:115], v[166:169], v[200:203], v[112:115]
	v_mfma_f32_16x16x32_bf16 v[108:111], v[158:161], v[208:211], v[108:111]
	v_mfma_f32_16x16x32_bf16 v[100:103], v[166:169], v[208:211], v[100:103]
	v_mfma_f32_16x16x32_bf16 v[76:79], v[158:161], v[216:219], v[76:79]
	v_mfma_f32_16x16x32_bf16 v[72:75], v[166:169], v[216:219], v[72:75]
	s_setprio 0
	s_setprio 1
	v_mfma_f32_16x16x32_bf16 v[104:107], v[172:175], v[188:191], v[104:107]
	v_mfma_f32_16x16x32_bf16 v[96:99], v[180:183], v[188:191], v[96:99]
	v_mfma_f32_16x16x32_bf16 v[92:95], v[172:175], v[196:199], v[92:95]
	v_mfma_f32_16x16x32_bf16 v[88:91], v[180:183], v[196:199], v[88:91]
	v_mfma_f32_16x16x32_bf16 v[84:87], v[172:175], v[204:207], v[84:87]
	v_mfma_f32_16x16x32_bf16 v[80:83], v[180:183], v[204:207], v[80:83]
	v_mfma_f32_16x16x32_bf16 v[68:71], v[172:175], v[212:215], v[68:71]
	v_mfma_f32_16x16x32_bf16 v[64:67], v[180:183], v[212:215], v[64:67]
	v_mfma_f32_16x16x32_bf16 v[104:107], v[176:179], v[192:195], v[104:107]
	v_mfma_f32_16x16x32_bf16 v[96:99], v[184:187], v[192:195], v[96:99]
	v_mfma_f32_16x16x32_bf16 v[92:95], v[176:179], v[200:203], v[92:95]
	v_mfma_f32_16x16x32_bf16 v[88:91], v[184:187], v[200:203], v[88:91]
	v_mfma_f32_16x16x32_bf16 v[84:87], v[176:179], v[208:211], v[84:87]
	v_mfma_f32_16x16x32_bf16 v[80:83], v[184:187], v[208:211], v[80:83]
	v_mfma_f32_16x16x32_bf16 v[68:71], v[176:179], v[216:219], v[68:71]
	v_mfma_f32_16x16x32_bf16 v[64:67], v[184:187], v[216:219], v[64:67]
	s_setprio 0
	s_barrier
	s_add_i32 s67, s54, s43
	v_lshl_add_u64 v[220:221], s[36:37], 0, v[132:133]
	s_mov_b32 m0, s67
	ds_read_b128 v[188:191], v152 offset:16384
	ds_read_b128 v[192:195], v152 offset:17408
	ds_read_b128 v[196:199], v152 offset:18432
	ds_read_b128 v[200:203], v152 offset:19456
	ds_read_b128 v[204:207], v152 offset:20480
	ds_read_b128 v[208:211], v152 offset:21504
	ds_read_b128 v[212:215], v152 offset:22528
	ds_read_b128 v[216:219], v152 offset:23552
	global_load_lds_dwordx4 v[220:221], off
	s_add_i32 m0, s67, 0x2000
	s_add_u32 s68, s36, 0x40000
	v_lshl_add_u64 v[222:223], s[36:37], 0, v[128:129]
	s_addc_u32 s69, s37, 0
	s_add_i32 s67, s55, s43
	global_load_lds_dwordx4 v[222:223], off
	v_lshl_add_u64 v[224:225], s[68:69], 0, v[132:133]
	s_mov_b32 m0, s67
	v_lshl_add_u64 v[226:227], s[38:39], 0, v[130:131]
	global_load_lds_dwordx4 v[224:225], off
	v_lshl_add_u64 v[224:225], s[68:69], 0, v[128:129]
	s_add_i32 m0, s67, 0x2000
	s_nop 0
	global_load_lds_dwordx4 v[224:225], off
	v_lshl_add_u64 v[224:225], s[38:39], 0, v[134:135]
	s_mov_b32 m0, s27
	s_nop 0
	global_load_lds_dwordx4 v[224:225], off
	s_mov_b32 m0, s46
	s_nop 0
	global_load_lds_dwordx4 v[226:227], off
	s_waitcnt vmcnt(8)
	s_waitcnt lgkmcnt(0)
	s_barrier
	s_setprio 1
	v_mfma_f32_16x16x32_bf16 v[60:63], v[154:157], v[188:191], v[60:63]
	v_mfma_f32_16x16x32_bf16 v[56:59], v[162:165], v[188:191], v[56:59]
	v_mfma_f32_16x16x32_bf16 v[52:55], v[154:157], v[196:199], v[52:55]
	v_mfma_f32_16x16x32_bf16 v[44:47], v[162:165], v[196:199], v[44:47]
	v_mfma_f32_16x16x32_bf16 v[36:39], v[154:157], v[204:207], v[36:39]
	v_mfma_f32_16x16x32_bf16 v[28:31], v[162:165], v[204:207], v[28:31]
	v_mfma_f32_16x16x32_bf16 v[20:23], v[154:157], v[212:215], v[20:23]
	v_mfma_f32_16x16x32_bf16 v[12:15], v[162:165], v[212:215], v[12:15]
	v_mfma_f32_16x16x32_bf16 v[60:63], v[158:161], v[192:195], v[60:63]
	v_mfma_f32_16x16x32_bf16 v[56:59], v[166:169], v[192:195], v[56:59]
	v_mfma_f32_16x16x32_bf16 v[52:55], v[158:161], v[200:203], v[52:55]
	v_mfma_f32_16x16x32_bf16 v[44:47], v[166:169], v[200:203], v[44:47]
	v_mfma_f32_16x16x32_bf16 v[36:39], v[158:161], v[208:211], v[36:39]
	v_mfma_f32_16x16x32_bf16 v[28:31], v[166:169], v[208:211], v[28:31]
	v_mfma_f32_16x16x32_bf16 v[20:23], v[158:161], v[216:219], v[20:23]
	v_mfma_f32_16x16x32_bf16 v[12:15], v[166:169], v[216:219], v[12:15]
	s_setprio 0
	s_setprio 1
	v_mfma_f32_16x16x32_bf16 v[48:51], v[172:175], v[188:191], v[48:51]
	v_mfma_f32_16x16x32_bf16 v[40:43], v[180:183], v[188:191], v[40:43]
	v_mfma_f32_16x16x32_bf16 v[32:35], v[172:175], v[196:199], v[32:35]
	v_mfma_f32_16x16x32_bf16 v[24:27], v[180:183], v[196:199], v[24:27]
	v_mfma_f32_16x16x32_bf16 v[16:19], v[172:175], v[204:207], v[16:19]
	v_mfma_f32_16x16x32_bf16 v[8:11], v[180:183], v[204:207], v[8:11]
	v_mfma_f32_16x16x32_bf16 v[4:7], v[172:175], v[212:215], v[4:7]
	v_mfma_f32_16x16x32_bf16 v[0:3], v[180:183], v[212:215], v[0:3]
	v_mfma_f32_16x16x32_bf16 v[48:51], v[176:179], v[192:195], v[48:51]
	v_mfma_f32_16x16x32_bf16 v[40:43], v[184:187], v[192:195], v[40:43]
	v_mfma_f32_16x16x32_bf16 v[32:35], v[176:179], v[200:203], v[32:35]
	v_mfma_f32_16x16x32_bf16 v[24:27], v[184:187], v[200:203], v[24:27]
	v_mfma_f32_16x16x32_bf16 v[16:19], v[176:179], v[208:211], v[16:19]
	v_mfma_f32_16x16x32_bf16 v[8:11], v[184:187], v[208:211], v[8:11]
	v_mfma_f32_16x16x32_bf16 v[4:7], v[176:179], v[216:219], v[4:7]
	v_mfma_f32_16x16x32_bf16 v[0:3], v[184:187], v[216:219], v[0:3]
	s_setprio 0
	s_barrier
	s_cmp_lg_u32 s66, 12
	s_cbranch_scc1 .Lmy_rs0_skip
	v_lshl_add_u32 v230, s26, 8, v147
	v_ashrrev_i32_e32 v231, 31, v230
	v_lshl_add_u64 v[232:233], v[230:231], 2, s[6:7]
	global_load_dword v230, v[232:233], off
	global_load_dword v234, v[232:233], off offset:128
	global_load_dword v236, v[232:233], off offset:192
	global_load_dword v238, v[232:233], off offset:512
	global_load_dword v240, v[232:233], off offset:576
	global_load_dword v242, v[232:233], off offset:640
	global_load_dword v244, v[232:233], off offset:704
	global_load_dword v232, v[232:233], off offset:64

.Lmy_rs0_wd:
	s_waitcnt lgkmcnt(0)
	s_barrier
	s_setprio 1
	v_mfma_f32_16x16x32_bf16 v[124:127], v[154:157], v[188:191], v[124:127]
	v_mfma_f32_16x16x32_bf16 v[120:123], v[162:165], v[188:191], v[120:123]
	v_mfma_f32_16x16x32_bf16 v[116:119], v[154:157], v[196:199], v[116:119]
	v_mfma_f32_16x16x32_bf16 v[112:115], v[162:165], v[196:199], v[112:115]
	v_mfma_f32_16x16x32_bf16 v[108:111], v[154:157], v[204:207], v[108:111]
	v_mfma_f32_16x16x32_bf16 v[100:103], v[162:165], v[204:207], v[100:103]
	v_mfma_f32_16x16x32_bf16 v[76:79], v[154:157], v[212:215], v[76:79]
	v_mfma_f32_16x16x32_bf16 v[72:75], v[162:165], v[212:215], v[72:75]
	v_mfma_f32_16x16x32_bf16 v[124:127], v[158:161], v[192:195], v[124:127]
	v_mfma_f32_16x16x32_bf16 v[120:123], v[166:169], v[192:195], v[120:123]
	v_mfma_f32_16x16x32_bf16 v[116:119], v[158:161], v[200:203], v[116:119]
	v_mfma_f32_16x16x32_bf16 v[112:115], v[166:169], v[200:203], v[112:115]
	v_mfma_f32_16x16x32_bf16 v[108:111], v[158:161], v[208:211], v[108:111]
	v_mfma_f32_16x16x32_bf16 v[100:103], v[166:169], v[208:211], v[100:103]
	v_mfma_f32_16x16x32_bf16 v[76:79], v[158:161], v[216:219], v[76:79]
	v_mfma_f32_16x16x32_bf16 v[72:75], v[166:169], v[216:219], v[72:75]
	s_setprio 0
	s_setprio 1
	v_mfma_f32_16x16x32_bf16 v[104:107], v[172:175], v[188:191], v[104:107]
	v_mfma_f32_16x16x32_bf16 v[96:99], v[180:183], v[188:191], v[96:99]
	v_mfma_f32_16x16x32_bf16 v[92:95], v[172:175], v[196:199], v[92:95]
	v_mfma_f32_16x16x32_bf16 v[88:91], v[180:183], v[196:199], v[88:91]
	v_mfma_f32_16x16x32_bf16 v[84:87], v[172:175], v[204:207], v[84:87]
	v_mfma_f32_16x16x32_bf16 v[80:83], v[180:183], v[204:207], v[80:83]
	v_mfma_f32_16x16x32_bf16 v[68:71], v[172:175], v[212:215], v[68:71]
	v_mfma_f32_16x16x32_bf16 v[64:67], v[180:183], v[212:215], v[64:67]
	v_mfma_f32_16x16x32_bf16 v[104:107], v[176:179], v[192:195], v[104:107]
	v_mfma_f32_16x16x32_bf16 v[96:99], v[184:187], v[192:195], v[96:99]
	v_mfma_f32_16x16x32_bf16 v[92:95], v[176:179], v[200:203], v[92:95]
	v_mfma_f32_16x16x32_bf16 v[88:91], v[184:187], v[200:203], v[88:91]
	v_mfma_f32_16x16x32_bf16 v[84:87], v[176:179], v[208:211], v[84:87]
	v_mfma_f32_16x16x32_bf16 v[80:83], v[184:187], v[208:211], v[80:83]
	v_mfma_f32_16x16x32_bf16 v[68:71], v[176:179], v[216:219], v[68:71]
	v_mfma_f32_16x16x32_bf16 v[64:67], v[184:187], v[216:219], v[64:67]
	s_setprio 0
	s_barrier
	s_add_i32 s38, s67, s43
	v_lshl_add_u64 v[220:221], v[220:221], 0, s[8:9]
	s_mov_b32 m0, s38
	ds_read_b128 v[188:191], v152 offset:49152
	ds_read_b128 v[192:195], v152 offset:50176
	ds_read_b128 v[196:199], v152 offset:51200
	ds_read_b128 v[200:203], v152 offset:52224
	ds_read_b128 v[204:207], v152 offset:53248
	ds_read_b128 v[208:211], v152 offset:54272
	ds_read_b128 v[212:215], v152 offset:55296
	ds_read_b128 v[216:219], v152 offset:56320
	global_load_lds_dwordx4 v[220:221], off
	s_add_i32 m0, s38, 0x2000
	s_add_u32 s36, s36, 0x40080
	v_lshl_add_u64 v[220:221], v[222:223], 0, s[8:9]
	s_addc_u32 s37, s37, 0
	s_add_i32 s38, s68, s43
	global_load_lds_dwordx4 v[220:221], off
	v_lshl_add_u64 v[220:221], s[36:37], 0, v[132:133]
	s_mov_b32 m0, s38
	s_nop 0
	global_load_lds_dwordx4 v[220:221], off
	v_lshl_add_u64 v[220:221], s[36:37], 0, v[128:129]
	s_add_i32 m0, s38, 0x2000
	s_nop 0
	global_load_lds_dwordx4 v[220:221], off
	v_lshl_add_u64 v[220:221], v[224:225], 0, s[8:9]
	s_mov_b32 m0, s50
	s_nop 0
	global_load_lds_dwordx4 v[220:221], off
	v_lshl_add_u64 v[220:221], v[226:227], 0, s[8:9]
	s_mov_b32 m0, s51
	s_nop 0
	global_load_lds_dwordx4 v[220:221], off
	s_waitcnt vmcnt(8)
	s_waitcnt lgkmcnt(0)
	s_barrier
	s_setprio 1
	v_mfma_f32_16x16x32_bf16 v[60:63], v[154:157], v[188:191], v[60:63]
	v_mfma_f32_16x16x32_bf16 v[56:59], v[162:165], v[188:191], v[56:59]
	v_mfma_f32_16x16x32_bf16 v[52:55], v[154:157], v[196:199], v[52:55]
	v_mfma_f32_16x16x32_bf16 v[44:47], v[162:165], v[196:199], v[44:47]
	v_mfma_f32_16x16x32_bf16 v[36:39], v[154:157], v[204:207], v[36:39]
	v_mfma_f32_16x16x32_bf16 v[28:31], v[162:165], v[204:207], v[28:31]
	v_mfma_f32_16x16x32_bf16 v[20:23], v[154:157], v[212:215], v[20:23]
	v_mfma_f32_16x16x32_bf16 v[12:15], v[162:165], v[212:215], v[12:15]
	v_mfma_f32_16x16x32_bf16 v[60:63], v[158:161], v[192:195], v[60:63]
	v_mfma_f32_16x16x32_bf16 v[56:59], v[166:169], v[192:195], v[56:59]
	v_mfma_f32_16x16x32_bf16 v[52:55], v[158:161], v[200:203], v[52:55]
	v_mfma_f32_16x16x32_bf16 v[44:47], v[166:169], v[200:203], v[44:47]
	v_mfma_f32_16x16x32_bf16 v[36:39], v[158:161], v[208:211], v[36:39]
	v_mfma_f32_16x16x32_bf16 v[28:31], v[166:169], v[208:211], v[28:31]
	v_mfma_f32_16x16x32_bf16 v[20:23], v[158:161], v[216:219], v[20:23]
	v_mfma_f32_16x16x32_bf16 v[12:15], v[166:169], v[216:219], v[12:15]
	s_setprio 0
	s_setprio 1
	v_mfma_f32_16x16x32_bf16 v[48:51], v[172:175], v[188:191], v[48:51]
	v_mfma_f32_16x16x32_bf16 v[40:43], v[180:183], v[188:191], v[40:43]
	v_mfma_f32_16x16x32_bf16 v[32:35], v[172:175], v[196:199], v[32:35]
	v_mfma_f32_16x16x32_bf16 v[24:27], v[180:183], v[196:199], v[24:27]
	v_mfma_f32_16x16x32_bf16 v[16:19], v[172:175], v[204:207], v[16:19]
	v_mfma_f32_16x16x32_bf16 v[8:11], v[180:183], v[204:207], v[8:11]
	v_mfma_f32_16x16x32_bf16 v[4:7], v[172:175], v[212:215], v[4:7]
	v_mfma_f32_16x16x32_bf16 v[0:3], v[180:183], v[212:215], v[0:3]
	v_mfma_f32_16x16x32_bf16 v[48:51], v[176:179], v[192:195], v[48:51]
	v_mfma_f32_16x16x32_bf16 v[40:43], v[184:187], v[192:195], v[40:43]
	v_mfma_f32_16x16x32_bf16 v[32:35], v[176:179], v[200:203], v[32:35]
	v_mfma_f32_16x16x32_bf16 v[24:27], v[184:187], v[200:203], v[24:27]
	v_mfma_f32_16x16x32_bf16 v[16:19], v[176:179], v[208:211], v[16:19]
	v_mfma_f32_16x16x32_bf16 v[8:11], v[184:187], v[208:211], v[8:11]
	v_mfma_f32_16x16x32_bf16 v[4:7], v[176:179], v[216:219], v[4:7]
	v_mfma_f32_16x16x32_bf16 v[0:3], v[184:187], v[216:219], v[0:3]
	s_setprio 0
	s_barrier
	s_add_i32 s66, s66, 2
	s_add_u32 s34, s34, 0x100
	s_addc_u32 s35, s35, 0
	s_add_u32 s64, s64, 0x100
	s_addc_u32 s65, s65, 0
	s_cmp_gt_u32 s66, 13
	s_cbranch_scc0 .LBB0_236
	s_and_b64 vcc, exec, s[10:11]
	s_cbranch_vccz .LBB0_239
	s_barrier

.LBB0_445:
	ds_read_b128 v[146:149], v167
	ds_read_b128 v[150:153], v167 offset:1024
	ds_read_b128 v[154:157], v167 offset:2048
	ds_read_b128 v[158:161], v167 offset:3072
	ds_read_b128 v[172:175], v168
	ds_read_b128 v[176:179], v168 offset:1024
	ds_read_b128 v[180:183], v168 offset:2048
	ds_read_b128 v[184:187], v168 offset:3072
	s_add_u32 s48, s46, 0xfffc0080
	s_addc_u32 s49, s47, -1
	s_cmp_eq_u32 s73, 12
	s_cselect_b32 s51, s1, s49
	s_cselect_b32 s50, s39, s48
	s_cselect_b32 s49, s37, s72
	s_cselect_b32 s48, s52, s53
	v_lshl_add_u64 v[162:163], s[46:47], 0, v[138:139]
	s_add_i32 m0, s45, 0xc000
	ds_read_b128 v[188:191], v169
	ds_read_b128 v[192:195], v169 offset:1024
	ds_read_b128 v[196:199], v169 offset:2048
	ds_read_b128 v[200:203], v169 offset:3072
	ds_read_b128 v[204:207], v169 offset:4096
	ds_read_b128 v[208:211], v169 offset:5120
	ds_read_b128 v[212:215], v169 offset:6144
	ds_read_b128 v[216:219], v169 offset:7168
	global_load_lds_dwordx4 v[162:163], off
	v_lshl_add_u64 v[162:163], s[46:47], 0, v[140:141]
	s_add_i32 m0, s45, 0xe000
	s_nop 0
	global_load_lds_dwordx4 v[162:163], off
	s_waitcnt vmcnt(8)
	s_waitcnt lgkmcnt(0)
	s_barrier
	s_setprio 1
	v_mfma_f32_16x16x32_bf16 v[124:127], v[146:149], v[188:191], v[124:127]
	v_mfma_f32_16x16x32_bf16 v[120:123], v[154:157], v[188:191], v[120:123]
	v_mfma_f32_16x16x32_bf16 v[108:111], v[146:149], v[196:199], v[108:111]
	v_mfma_f32_16x16x32_bf16 v[104:107], v[154:157], v[196:199], v[104:107]
	v_mfma_f32_16x16x32_bf16 v[92:95], v[146:149], v[204:207], v[92:95]
	v_mfma_f32_16x16x32_bf16 v[88:91], v[154:157], v[204:207], v[88:91]
	v_mfma_f32_16x16x32_bf16 v[76:79], v[146:149], v[212:215], v[76:79]
	v_mfma_f32_16x16x32_bf16 v[72:75], v[154:157], v[212:215], v[72:75]
	v_mfma_f32_16x16x32_bf16 v[124:127], v[150:153], v[192:195], v[124:127]
	v_mfma_f32_16x16x32_bf16 v[120:123], v[158:161], v[192:195], v[120:123]
	v_mfma_f32_16x16x32_bf16 v[108:111], v[150:153], v[200:203], v[108:111]
	v_mfma_f32_16x16x32_bf16 v[104:107], v[158:161], v[200:203], v[104:107]
	v_mfma_f32_16x16x32_bf16 v[92:95], v[150:153], v[208:211], v[92:95]
	v_mfma_f32_16x16x32_bf16 v[88:91], v[158:161], v[208:211], v[88:91]
	v_mfma_f32_16x16x32_bf16 v[76:79], v[150:153], v[216:219], v[76:79]
	v_mfma_f32_16x16x32_bf16 v[72:75], v[158:161], v[216:219], v[72:75]
	s_setprio 0
	s_setprio 1
	v_mfma_f32_16x16x32_bf16 v[116:119], v[172:175], v[188:191], v[116:119]
	v_mfma_f32_16x16x32_bf16 v[112:115], v[180:183], v[188:191], v[112:115]
	v_mfma_f32_16x16x32_bf16 v[100:103], v[172:175], v[196:199], v[100:103]
	v_mfma_f32_16x16x32_bf16 v[96:99], v[180:183], v[196:199], v[96:99]
	v_mfma_f32_16x16x32_bf16 v[84:87], v[172:175], v[204:207], v[84:87]
	v_mfma_f32_16x16x32_bf16 v[80:83], v[180:183], v[204:207], v[80:83]
	v_mfma_f32_16x16x32_bf16 v[68:71], v[172:175], v[212:215], v[68:71]
	v_mfma_f32_16x16x32_bf16 v[64:67], v[180:183], v[212:215], v[64:67]
	v_mfma_f32_16x16x32_bf16 v[116:119], v[176:179], v[192:195], v[116:119]
	v_mfma_f32_16x16x32_bf16 v[112:115], v[184:187], v[192:195], v[112:115]
	v_mfma_f32_16x16x32_bf16 v[100:103], v[176:179], v[200:203], v[100:103]
	v_mfma_f32_16x16x32_bf16 v[96:99], v[184:187], v[200:203], v[96:99]
	v_mfma_f32_16x16x32_bf16 v[84:87], v[176:179], v[208:211], v[84:87]
	v_mfma_f32_16x16x32_bf16 v[80:83], v[184:187], v[208:211], v[80:83]
	v_mfma_f32_16x16x32_bf16 v[68:71], v[176:179], v[216:219], v[68:71]
	v_mfma_f32_16x16x32_bf16 v[64:67], v[184:187], v[216:219], v[64:67]
	s_setprio 0
	s_barrier
	s_add_i32 s74, s66, s57
	v_lshl_add_u64 v[162:163], s[48:49], 0, v[130:131]
	s_mov_b32 m0, s74
	ds_read_b128 v[188:191], v169 offset:16384
	ds_read_b128 v[192:195], v169 offset:17408
	ds_read_b128 v[196:199], v169 offset:18432
	ds_read_b128 v[200:203], v169 offset:19456
	ds_read_b128 v[204:207], v169 offset:20480
	ds_read_b128 v[208:211], v169 offset:21504
	ds_read_b128 v[212:215], v169 offset:22528
	ds_read_b128 v[216:219], v169 offset:23552
	global_load_lds_dwordx4 v[162:163], off
	s_add_i32 m0, s74, 0x2000
	s_add_u32 s74, s48, 0x40000
	v_lshl_add_u64 v[220:221], s[48:49], 0, v[134:135]
	s_addc_u32 s75, s49, 0
	s_add_i32 s76, s67, s57
	global_load_lds_dwordx4 v[220:221], off
	v_lshl_add_u64 v[222:223], s[74:75], 0, v[130:131]
	s_mov_b32 m0, s76
	v_lshl_add_u64 v[224:225], s[50:51], 0, v[132:133]
	global_load_lds_dwordx4 v[222:223], off
	v_lshl_add_u64 v[222:223], s[74:75], 0, v[134:135]
	s_add_i32 m0, s76, 0x2000
	s_nop 0
	global_load_lds_dwordx4 v[222:223], off
	v_lshl_add_u64 v[222:223], s[50:51], 0, v[128:129]
	s_mov_b32 m0, s45
	s_nop 0
	global_load_lds_dwordx4 v[222:223], off
	s_mov_b32 m0, s58
	s_nop 0
	global_load_lds_dwordx4 v[224:225], off
	s_waitcnt vmcnt(8)
	s_waitcnt lgkmcnt(0)
	s_barrier
	s_setprio 1
	v_mfma_f32_16x16x32_bf16 v[60:63], v[146:149], v[188:191], v[60:63]
	v_mfma_f32_16x16x32_bf16 v[56:59], v[154:157], v[188:191], v[56:59]
	v_mfma_f32_16x16x32_bf16 v[44:47], v[146:149], v[196:199], v[44:47]
	v_mfma_f32_16x16x32_bf16 v[40:43], v[154:157], v[196:199], v[40:43]
	v_mfma_f32_16x16x32_bf16 v[28:31], v[146:149], v[204:207], v[28:31]
	v_mfma_f32_16x16x32_bf16 v[24:27], v[154:157], v[204:207], v[24:27]
	v_mfma_f32_16x16x32_bf16 v[12:15], v[146:149], v[212:215], v[12:15]
	v_mfma_f32_16x16x32_bf16 v[8:11], v[154:157], v[212:215], v[8:11]
	v_mfma_f32_16x16x32_bf16 v[60:63], v[150:153], v[192:195], v[60:63]
	v_mfma_f32_16x16x32_bf16 v[56:59], v[158:161], v[192:195], v[56:59]
	v_mfma_f32_16x16x32_bf16 v[44:47], v[150:153], v[200:203], v[44:47]
	v_mfma_f32_16x16x32_bf16 v[40:43], v[158:161], v[200:203], v[40:43]
	v_mfma_f32_16x16x32_bf16 v[28:31], v[150:153], v[208:211], v[28:31]
	v_mfma_f32_16x16x32_bf16 v[24:27], v[158:161], v[208:211], v[24:27]
	v_mfma_f32_16x16x32_bf16 v[12:15], v[150:153], v[216:219], v[12:15]
	v_mfma_f32_16x16x32_bf16 v[8:11], v[158:161], v[216:219], v[8:11]
	s_setprio 0
	s_setprio 1
	v_mfma_f32_16x16x32_bf16 v[52:55], v[172:175], v[188:191], v[52:55]
	v_mfma_f32_16x16x32_bf16 v[48:51], v[180:183], v[188:191], v[48:51]
	v_mfma_f32_16x16x32_bf16 v[36:39], v[172:175], v[196:199], v[36:39]
	v_mfma_f32_16x16x32_bf16 v[32:35], v[180:183], v[196:199], v[32:35]
	v_mfma_f32_16x16x32_bf16 v[20:23], v[172:175], v[204:207], v[20:23]
	v_mfma_f32_16x16x32_bf16 v[16:19], v[180:183], v[204:207], v[16:19]
	v_mfma_f32_16x16x32_bf16 v[4:7], v[172:175], v[212:215], v[4:7]
	v_mfma_f32_16x16x32_bf16 v[0:3], v[180:183], v[212:215], v[0:3]
	v_mfma_f32_16x16x32_bf16 v[52:55], v[176:179], v[192:195], v[52:55]
	v_mfma_f32_16x16x32_bf16 v[48:51], v[184:187], v[192:195], v[48:51]
	v_mfma_f32_16x16x32_bf16 v[36:39], v[176:179], v[200:203], v[36:39]
	v_mfma_f32_16x16x32_bf16 v[32:35], v[184:187], v[200:203], v[32:35]
	v_mfma_f32_16x16x32_bf16 v[20:23], v[176:179], v[208:211], v[20:23]
	v_mfma_f32_16x16x32_bf16 v[16:19], v[184:187], v[208:211], v[16:19]
	v_mfma_f32_16x16x32_bf16 v[4:7], v[176:179], v[216:219], v[4:7]
	v_mfma_f32_16x16x32_bf16 v[0:3], v[184:187], v[216:219], v[0:3]
	s_setprio 0
	s_barrier
	s_cmp_lg_u32 s73, 12
	s_cbranch_scc1 .Lmy_rs5_skip
	v_lshl_add_u32 v230, s0, 8, v164
	v_ashrrev_i32_e32 v231, 31, v230
	v_lshl_add_u64 v[232:233], v[230:231], 2, s[16:17]
	global_load_dword v230, v[232:233], off
	global_load_dword v234, v[232:233], off offset:128
	global_load_dword v236, v[232:233], off offset:192
	global_load_dword v238, v[232:233], off offset:512
	global_load_dword v240, v[232:233], off offset:576
	global_load_dword v242, v[232:233], off offset:640
	global_load_dword v244, v[232:233], off offset:704
	global_load_dword v232, v[232:233], off offset:64

.Lmy_rs5_wd:
	s_waitcnt lgkmcnt(0)
	s_barrier
	s_setprio 1
	v_mfma_f32_16x16x32_bf16 v[124:127], v[146:149], v[188:191], v[124:127]
	v_mfma_f32_16x16x32_bf16 v[120:123], v[154:157], v[188:191], v[120:123]
	v_mfma_f32_16x16x32_bf16 v[108:111], v[146:149], v[196:199], v[108:111]
	v_mfma_f32_16x16x32_bf16 v[104:107], v[154:157], v[196:199], v[104:107]
	v_mfma_f32_16x16x32_bf16 v[92:95], v[146:149], v[204:207], v[92:95]
	v_mfma_f32_16x16x32_bf16 v[88:91], v[154:157], v[204:207], v[88:91]
	v_mfma_f32_16x16x32_bf16 v[76:79], v[146:149], v[212:215], v[76:79]
	v_mfma_f32_16x16x32_bf16 v[72:75], v[154:157], v[212:215], v[72:75]
	v_mfma_f32_16x16x32_bf16 v[124:127], v[150:153], v[192:195], v[124:127]
	v_mfma_f32_16x16x32_bf16 v[120:123], v[158:161], v[192:195], v[120:123]
	v_mfma_f32_16x16x32_bf16 v[108:111], v[150:153], v[200:203], v[108:111]
	v_mfma_f32_16x16x32_bf16 v[104:107], v[158:161], v[200:203], v[104:107]
	v_mfma_f32_16x16x32_bf16 v[92:95], v[150:153], v[208:211], v[92:95]
	v_mfma_f32_16x16x32_bf16 v[88:91], v[158:161], v[208:211], v[88:91]
	v_mfma_f32_16x16x32_bf16 v[76:79], v[150:153], v[216:219], v[76:79]
	v_mfma_f32_16x16x32_bf16 v[72:75], v[158:161], v[216:219], v[72:75]
	s_setprio 0
	s_setprio 1
	v_mfma_f32_16x16x32_bf16 v[116:119], v[172:175], v[188:191], v[116:119]
	v_mfma_f32_16x16x32_bf16 v[112:115], v[180:183], v[188:191], v[112:115]
	v_mfma_f32_16x16x32_bf16 v[100:103], v[172:175], v[196:199], v[100:103]
	v_mfma_f32_16x16x32_bf16 v[96:99], v[180:183], v[196:199], v[96:99]
	v_mfma_f32_16x16x32_bf16 v[84:87], v[172:175], v[204:207], v[84:87]
	v_mfma_f32_16x16x32_bf16 v[80:83], v[180:183], v[204:207], v[80:83]
	v_mfma_f32_16x16x32_bf16 v[68:71], v[172:175], v[212:215], v[68:71]
	v_mfma_f32_16x16x32_bf16 v[64:67], v[180:183], v[212:215], v[64:67]
	v_mfma_f32_16x16x32_bf16 v[116:119], v[176:179], v[192:195], v[116:119]
	v_mfma_f32_16x16x32_bf16 v[112:115], v[184:187], v[192:195], v[112:115]
	v_mfma_f32_16x16x32_bf16 v[100:103], v[176:179], v[200:203], v[100:103]
	v_mfma_f32_16x16x32_bf16 v[96:99], v[184:187], v[200:203], v[96:99]
	v_mfma_f32_16x16x32_bf16 v[84:87], v[176:179], v[208:211], v[84:87]
	v_mfma_f32_16x16x32_bf16 v[80:83], v[184:187], v[208:211], v[80:83]
	v_mfma_f32_16x16x32_bf16 v[68:71], v[176:179], v[216:219], v[68:71]
	v_mfma_f32_16x16x32_bf16 v[64:67], v[184:187], v[216:219], v[64:67]
	s_setprio 0
	s_barrier
	s_add_i32 s50, s74, s57
	v_lshl_add_u64 v[162:163], v[162:163], 0, s[18:19]
	s_mov_b32 m0, s50
	ds_read_b128 v[188:191], v169 offset:49152
	ds_read_b128 v[192:195], v169 offset:50176
	ds_read_b128 v[196:199], v169 offset:51200
	ds_read_b128 v[200:203], v169 offset:52224
	ds_read_b128 v[204:207], v169 offset:53248
	ds_read_b128 v[208:211], v169 offset:54272
	ds_read_b128 v[212:215], v169 offset:55296
	ds_read_b128 v[216:219], v169 offset:56320
	global_load_lds_dwordx4 v[162:163], off
	s_add_i32 m0, s50, 0x2000
	s_add_u32 s48, s48, 0x40080
	v_lshl_add_u64 v[162:163], v[220:221], 0, s[18:19]
	s_addc_u32 s49, s49, 0
	s_add_i32 s50, s75, s57
	global_load_lds_dwordx4 v[162:163], off
	v_lshl_add_u64 v[162:163], s[48:49], 0, v[130:131]
	s_mov_b32 m0, s50
	s_nop 0
	global_load_lds_dwordx4 v[162:163], off
	v_lshl_add_u64 v[162:163], s[48:49], 0, v[134:135]
	s_add_i32 m0, s50, 0x2000
	s_nop 0
	global_load_lds_dwordx4 v[162:163], off
	v_lshl_add_u64 v[162:163], v[222:223], 0, s[18:19]
	s_mov_b32 m0, s33
	s_nop 0
	global_load_lds_dwordx4 v[162:163], off
	v_lshl_add_u64 v[162:163], v[224:225], 0, s[18:19]
	s_mov_b32 m0, s62
	s_nop 0
	global_load_lds_dwordx4 v[162:163], off
	s_waitcnt vmcnt(8)
	s_waitcnt lgkmcnt(0)
	s_barrier
	s_setprio 1
	v_mfma_f32_16x16x32_bf16 v[60:63], v[146:149], v[188:191], v[60:63]
	v_mfma_f32_16x16x32_bf16 v[56:59], v[154:157], v[188:191], v[56:59]
	v_mfma_f32_16x16x32_bf16 v[44:47], v[146:149], v[196:199], v[44:47]
	v_mfma_f32_16x16x32_bf16 v[40:43], v[154:157], v[196:199], v[40:43]
	v_mfma_f32_16x16x32_bf16 v[28:31], v[146:149], v[204:207], v[28:31]
	v_mfma_f32_16x16x32_bf16 v[24:27], v[154:157], v[204:207], v[24:27]
	v_mfma_f32_16x16x32_bf16 v[12:15], v[146:149], v[212:215], v[12:15]
	v_mfma_f32_16x16x32_bf16 v[8:11], v[154:157], v[212:215], v[8:11]
	v_mfma_f32_16x16x32_bf16 v[60:63], v[150:153], v[192:195], v[60:63]
	v_mfma_f32_16x16x32_bf16 v[56:59], v[158:161], v[192:195], v[56:59]
	v_mfma_f32_16x16x32_bf16 v[44:47], v[150:153], v[200:203], v[44:47]
	v_mfma_f32_16x16x32_bf16 v[40:43], v[158:161], v[200:203], v[40:43]
	v_mfma_f32_16x16x32_bf16 v[28:31], v[150:153], v[208:211], v[28:31]
	v_mfma_f32_16x16x32_bf16 v[24:27], v[158:161], v[208:211], v[24:27]
	v_mfma_f32_16x16x32_bf16 v[12:15], v[150:153], v[216:219], v[12:15]
	v_mfma_f32_16x16x32_bf16 v[8:11], v[158:161], v[216:219], v[8:11]
	s_setprio 0
	s_setprio 1
	v_mfma_f32_16x16x32_bf16 v[52:55], v[172:175], v[188:191], v[52:55]
	v_mfma_f32_16x16x32_bf16 v[48:51], v[180:183], v[188:191], v[48:51]
	v_mfma_f32_16x16x32_bf16 v[36:39], v[172:175], v[196:199], v[36:39]
	v_mfma_f32_16x16x32_bf16 v[32:35], v[180:183], v[196:199], v[32:35]
	v_mfma_f32_16x16x32_bf16 v[20:23], v[172:175], v[204:207], v[20:23]
	v_mfma_f32_16x16x32_bf16 v[16:19], v[180:183], v[204:207], v[16:19]
	v_mfma_f32_16x16x32_bf16 v[4:7], v[172:175], v[212:215], v[4:7]
	v_mfma_f32_16x16x32_bf16 v[0:3], v[180:183], v[212:215], v[0:3]
	v_mfma_f32_16x16x32_bf16 v[52:55], v[176:179], v[192:195], v[52:55]
	v_mfma_f32_16x16x32_bf16 v[48:51], v[184:187], v[192:195], v[48:51]
	v_mfma_f32_16x16x32_bf16 v[36:39], v[176:179], v[200:203], v[36:39]
	v_mfma_f32_16x16x32_bf16 v[32:35], v[184:187], v[200:203], v[32:35]
	v_mfma_f32_16x16x32_bf16 v[20:23], v[176:179], v[208:211], v[20:23]
	v_mfma_f32_16x16x32_bf16 v[16:19], v[184:187], v[208:211], v[16:19]
	v_mfma_f32_16x16x32_bf16 v[4:7], v[176:179], v[216:219], v[4:7]
	v_mfma_f32_16x16x32_bf16 v[0:3], v[184:187], v[216:219], v[0:3]
	s_setprio 0
	s_barrier
	s_add_i32 s73, s73, 2
	s_add_u32 s46, s46, 0x100
	s_addc_u32 s47, s47, 0
	s_add_u32 s53, s53, 0x100
	s_addc_u32 s72, s72, 0
	s_cmp_gt_u32 s73, 13
	s_cbranch_scc0 .LBB0_445
	s_and_b64 vcc, exec, s[20:21]
	s_cbranch_vccz .LBB0_448
	s_barrier

.LBB0_771:
	ds_read_b128 v[144:147], v174
	ds_read_b128 v[148:151], v174 offset:1024
	ds_read_b128 v[152:155], v174 offset:2048
	ds_read_b128 v[156:159], v174 offset:3072
	ds_read_b128 v[160:163], v175
	ds_read_b128 v[164:167], v175 offset:1024
	ds_read_b128 v[178:181], v175 offset:2048
	ds_read_b128 v[182:185], v175 offset:3072
	s_add_u32 s48, s46, 0xfffc0080
	s_addc_u32 s49, s47, -1
	s_cmp_eq_u32 s71, 12
	s_cselect_b32 s51, s1, s49
	s_cselect_b32 s50, s7, s48
	s_cselect_b32 s49, s33, s70
	s_cselect_b32 s48, s39, s41
	v_lshl_add_u64 v[168:169], s[46:47], 0, v[136:137]
	s_add_i32 m0, s56, 0xc000
	ds_read_b128 v[186:189], v176
	ds_read_b128 v[190:193], v176 offset:1024
	ds_read_b128 v[194:197], v176 offset:2048
	ds_read_b128 v[198:201], v176 offset:3072
	ds_read_b128 v[202:205], v176 offset:4096
	ds_read_b128 v[206:209], v176 offset:5120
	ds_read_b128 v[210:213], v176 offset:6144
	ds_read_b128 v[214:217], v176 offset:7168
	global_load_lds_dwordx4 v[168:169], off
	v_lshl_add_u64 v[168:169], s[46:47], 0, v[138:139]
	s_add_i32 m0, s56, 0xe000
	s_nop 0
	global_load_lds_dwordx4 v[168:169], off
	s_waitcnt vmcnt(8)
	s_waitcnt lgkmcnt(0)
	s_barrier
	s_setprio 1
	v_mfma_f32_16x16x32_bf16 v[124:127], v[144:147], v[186:189], v[124:127]
	v_mfma_f32_16x16x32_bf16 v[120:123], v[152:155], v[186:189], v[120:123]
	v_mfma_f32_16x16x32_bf16 v[108:111], v[144:147], v[194:197], v[108:111]
	v_mfma_f32_16x16x32_bf16 v[104:107], v[152:155], v[194:197], v[104:107]
	v_mfma_f32_16x16x32_bf16 v[92:95], v[144:147], v[202:205], v[92:95]
	v_mfma_f32_16x16x32_bf16 v[88:91], v[152:155], v[202:205], v[88:91]
	v_mfma_f32_16x16x32_bf16 v[76:79], v[144:147], v[210:213], v[76:79]
	v_mfma_f32_16x16x32_bf16 v[72:75], v[152:155], v[210:213], v[72:75]
	v_mfma_f32_16x16x32_bf16 v[124:127], v[148:151], v[190:193], v[124:127]
	v_mfma_f32_16x16x32_bf16 v[120:123], v[156:159], v[190:193], v[120:123]
	v_mfma_f32_16x16x32_bf16 v[108:111], v[148:151], v[198:201], v[108:111]
	v_mfma_f32_16x16x32_bf16 v[104:107], v[156:159], v[198:201], v[104:107]
	v_mfma_f32_16x16x32_bf16 v[92:95], v[148:151], v[206:209], v[92:95]
	v_mfma_f32_16x16x32_bf16 v[88:91], v[156:159], v[206:209], v[88:91]
	v_mfma_f32_16x16x32_bf16 v[76:79], v[148:151], v[214:217], v[76:79]
	v_mfma_f32_16x16x32_bf16 v[72:75], v[156:159], v[214:217], v[72:75]
	s_setprio 0
	s_setprio 1
	v_mfma_f32_16x16x32_bf16 v[116:119], v[160:163], v[186:189], v[116:119]
	v_mfma_f32_16x16x32_bf16 v[112:115], v[178:181], v[186:189], v[112:115]
	v_mfma_f32_16x16x32_bf16 v[100:103], v[160:163], v[194:197], v[100:103]
	v_mfma_f32_16x16x32_bf16 v[96:99], v[178:181], v[194:197], v[96:99]
	v_mfma_f32_16x16x32_bf16 v[84:87], v[160:163], v[202:205], v[84:87]
	v_mfma_f32_16x16x32_bf16 v[80:83], v[178:181], v[202:205], v[80:83]
	v_mfma_f32_16x16x32_bf16 v[68:71], v[160:163], v[210:213], v[68:71]
	v_mfma_f32_16x16x32_bf16 v[64:67], v[178:181], v[210:213], v[64:67]
	v_mfma_f32_16x16x32_bf16 v[116:119], v[164:167], v[190:193], v[116:119]
	v_mfma_f32_16x16x32_bf16 v[112:115], v[182:185], v[190:193], v[112:115]
	v_mfma_f32_16x16x32_bf16 v[100:103], v[164:167], v[198:201], v[100:103]
	v_mfma_f32_16x16x32_bf16 v[96:99], v[182:185], v[198:201], v[96:99]
	v_mfma_f32_16x16x32_bf16 v[84:87], v[164:167], v[206:209], v[84:87]
	v_mfma_f32_16x16x32_bf16 v[80:83], v[182:185], v[206:209], v[80:83]
	v_mfma_f32_16x16x32_bf16 v[68:71], v[164:167], v[214:217], v[68:71]
	v_mfma_f32_16x16x32_bf16 v[64:67], v[182:185], v[214:217], v[64:67]
	s_setprio 0
	s_barrier
	s_add_i32 s72, s67, s55
	v_lshl_add_u64 v[168:169], s[48:49], 0, v[130:131]
	s_mov_b32 m0, s72
	ds_read_b128 v[186:189], v176 offset:16384
	ds_read_b128 v[190:193], v176 offset:17408
	ds_read_b128 v[194:197], v176 offset:18432
	ds_read_b128 v[198:201], v176 offset:19456
	ds_read_b128 v[202:205], v176 offset:20480
	ds_read_b128 v[206:209], v176 offset:21504
	ds_read_b128 v[210:213], v176 offset:22528
	ds_read_b128 v[214:217], v176 offset:23552
	global_load_lds_dwordx4 v[168:169], off
	s_add_i32 m0, s72, 0x2000
	s_add_u32 s72, s48, 0x40000
	v_lshl_add_u64 v[218:219], s[48:49], 0, v[134:135]
	s_addc_u32 s73, s49, 0
	s_add_i32 s74, s68, s55
	global_load_lds_dwordx4 v[218:219], off
	v_lshl_add_u64 v[220:221], s[72:73], 0, v[130:131]
	s_mov_b32 m0, s74
	v_lshl_add_u64 v[222:223], s[50:51], 0, v[132:133]
	global_load_lds_dwordx4 v[220:221], off
	v_lshl_add_u64 v[220:221], s[72:73], 0, v[134:135]
	s_add_i32 m0, s74, 0x2000
	s_nop 0
	global_load_lds_dwordx4 v[220:221], off
	v_lshl_add_u64 v[220:221], s[50:51], 0, v[128:129]
	s_mov_b32 m0, s56
	s_nop 0
	global_load_lds_dwordx4 v[220:221], off
	s_mov_b32 m0, s57
	s_nop 0
	global_load_lds_dwordx4 v[222:223], off
	s_waitcnt vmcnt(8)
	s_waitcnt lgkmcnt(0)
	s_barrier
	s_setprio 1
	v_mfma_f32_16x16x32_bf16 v[60:63], v[144:147], v[186:189], v[60:63]
	v_mfma_f32_16x16x32_bf16 v[56:59], v[152:155], v[186:189], v[56:59]
	v_mfma_f32_16x16x32_bf16 v[44:47], v[144:147], v[194:197], v[44:47]
	v_mfma_f32_16x16x32_bf16 v[40:43], v[152:155], v[194:197], v[40:43]
	v_mfma_f32_16x16x32_bf16 v[28:31], v[144:147], v[202:205], v[28:31]
	v_mfma_f32_16x16x32_bf16 v[24:27], v[152:155], v[202:205], v[24:27]
	v_mfma_f32_16x16x32_bf16 v[12:15], v[144:147], v[210:213], v[12:15]
	v_mfma_f32_16x16x32_bf16 v[8:11], v[152:155], v[210:213], v[8:11]
	v_mfma_f32_16x16x32_bf16 v[60:63], v[148:151], v[190:193], v[60:63]
	v_mfma_f32_16x16x32_bf16 v[56:59], v[156:159], v[190:193], v[56:59]
	v_mfma_f32_16x16x32_bf16 v[44:47], v[148:151], v[198:201], v[44:47]
	v_mfma_f32_16x16x32_bf16 v[40:43], v[156:159], v[198:201], v[40:43]
	v_mfma_f32_16x16x32_bf16 v[28:31], v[148:151], v[206:209], v[28:31]
	v_mfma_f32_16x16x32_bf16 v[24:27], v[156:159], v[206:209], v[24:27]
	v_mfma_f32_16x16x32_bf16 v[12:15], v[148:151], v[214:217], v[12:15]
	v_mfma_f32_16x16x32_bf16 v[8:11], v[156:159], v[214:217], v[8:11]
	s_setprio 0
	s_setprio 1
	v_mfma_f32_16x16x32_bf16 v[52:55], v[160:163], v[186:189], v[52:55]
	v_mfma_f32_16x16x32_bf16 v[48:51], v[178:181], v[186:189], v[48:51]
	v_mfma_f32_16x16x32_bf16 v[36:39], v[160:163], v[194:197], v[36:39]
	v_mfma_f32_16x16x32_bf16 v[32:35], v[178:181], v[194:197], v[32:35]
	v_mfma_f32_16x16x32_bf16 v[20:23], v[160:163], v[202:205], v[20:23]
	v_mfma_f32_16x16x32_bf16 v[16:19], v[178:181], v[202:205], v[16:19]
	v_mfma_f32_16x16x32_bf16 v[4:7], v[160:163], v[210:213], v[4:7]
	v_mfma_f32_16x16x32_bf16 v[0:3], v[178:181], v[210:213], v[0:3]
	v_mfma_f32_16x16x32_bf16 v[52:55], v[164:167], v[190:193], v[52:55]
	v_mfma_f32_16x16x32_bf16 v[48:51], v[182:185], v[190:193], v[48:51]
	v_mfma_f32_16x16x32_bf16 v[36:39], v[164:167], v[198:201], v[36:39]
	v_mfma_f32_16x16x32_bf16 v[32:35], v[182:185], v[198:201], v[32:35]
	v_mfma_f32_16x16x32_bf16 v[20:23], v[164:167], v[206:209], v[20:23]
	v_mfma_f32_16x16x32_bf16 v[16:19], v[182:185], v[206:209], v[16:19]
	v_mfma_f32_16x16x32_bf16 v[4:7], v[164:167], v[214:217], v[4:7]
	v_mfma_f32_16x16x32_bf16 v[0:3], v[182:185], v[214:217], v[0:3]
	s_setprio 0
	s_barrier
	s_cmp_lg_u32 s71, 12
	s_cbranch_scc1 .Lmy_rs8_skip
	v_lshl_add_u32 v230, s6, 8, v171
	v_ashrrev_i32_e32 v231, 31, v230
	v_lshl_add_u64 v[232:233], v[230:231], 2, s[12:13]
	global_load_dword v230, v[232:233], off
	global_load_dword v234, v[232:233], off offset:128
	global_load_dword v236, v[232:233], off offset:192
	global_load_dword v238, v[232:233], off offset:512
	global_load_dword v240, v[232:233], off offset:576
	global_load_dword v242, v[232:233], off offset:640
	global_load_dword v244, v[232:233], off offset:704
	global_load_dword v232, v[232:233], off offset:64

.Lmy_rs8_wd:
	s_waitcnt lgkmcnt(0)
	s_barrier
	s_setprio 1
	v_mfma_f32_16x16x32_bf16 v[124:127], v[144:147], v[186:189], v[124:127]
	v_mfma_f32_16x16x32_bf16 v[120:123], v[152:155], v[186:189], v[120:123]
	v_mfma_f32_16x16x32_bf16 v[108:111], v[144:147], v[194:197], v[108:111]
	v_mfma_f32_16x16x32_bf16 v[104:107], v[152:155], v[194:197], v[104:107]
	v_mfma_f32_16x16x32_bf16 v[92:95], v[144:147], v[202:205], v[92:95]
	v_mfma_f32_16x16x32_bf16 v[88:91], v[152:155], v[202:205], v[88:91]
	v_mfma_f32_16x16x32_bf16 v[76:79], v[144:147], v[210:213], v[76:79]
	v_mfma_f32_16x16x32_bf16 v[72:75], v[152:155], v[210:213], v[72:75]
	v_mfma_f32_16x16x32_bf16 v[124:127], v[148:151], v[190:193], v[124:127]
	v_mfma_f32_16x16x32_bf16 v[120:123], v[156:159], v[190:193], v[120:123]
	v_mfma_f32_16x16x32_bf16 v[108:111], v[148:151], v[198:201], v[108:111]
	v_mfma_f32_16x16x32_bf16 v[104:107], v[156:159], v[198:201], v[104:107]
	v_mfma_f32_16x16x32_bf16 v[92:95], v[148:151], v[206:209], v[92:95]
	v_mfma_f32_16x16x32_bf16 v[88:91], v[156:159], v[206:209], v[88:91]
	v_mfma_f32_16x16x32_bf16 v[76:79], v[148:151], v[214:217], v[76:79]
	v_mfma_f32_16x16x32_bf16 v[72:75], v[156:159], v[214:217], v[72:75]
	s_setprio 0
	s_setprio 1
	v_mfma_f32_16x16x32_bf16 v[116:119], v[160:163], v[186:189], v[116:119]
	v_mfma_f32_16x16x32_bf16 v[112:115], v[178:181], v[186:189], v[112:115]
	v_mfma_f32_16x16x32_bf16 v[100:103], v[160:163], v[194:197], v[100:103]
	v_mfma_f32_16x16x32_bf16 v[96:99], v[178:181], v[194:197], v[96:99]
	v_mfma_f32_16x16x32_bf16 v[84:87], v[160:163], v[202:205], v[84:87]
	v_mfma_f32_16x16x32_bf16 v[80:83], v[178:181], v[202:205], v[80:83]
	v_mfma_f32_16x16x32_bf16 v[68:71], v[160:163], v[210:213], v[68:71]
	v_mfma_f32_16x16x32_bf16 v[64:67], v[178:181], v[210:213], v[64:67]
	v_mfma_f32_16x16x32_bf16 v[116:119], v[164:167], v[190:193], v[116:119]
	v_mfma_f32_16x16x32_bf16 v[112:115], v[182:185], v[190:193], v[112:115]
	v_mfma_f32_16x16x32_bf16 v[100:103], v[164:167], v[198:201], v[100:103]
	v_mfma_f32_16x16x32_bf16 v[96:99], v[182:185], v[198:201], v[96:99]
	v_mfma_f32_16x16x32_bf16 v[84:87], v[164:167], v[206:209], v[84:87]
	v_mfma_f32_16x16x32_bf16 v[80:83], v[182:185], v[206:209], v[80:83]
	v_mfma_f32_16x16x32_bf16 v[68:71], v[164:167], v[214:217], v[68:71]
	v_mfma_f32_16x16x32_bf16 v[64:67], v[182:185], v[214:217], v[64:67]
	s_setprio 0
	s_barrier
	s_add_i32 s50, s72, s55
	v_lshl_add_u64 v[168:169], v[168:169], 0, s[16:17]
	s_mov_b32 m0, s50
	ds_read_b128 v[186:189], v176 offset:49152
	ds_read_b128 v[190:193], v176 offset:50176
	ds_read_b128 v[194:197], v176 offset:51200
	ds_read_b128 v[198:201], v176 offset:52224
	ds_read_b128 v[202:205], v176 offset:53248
	ds_read_b128 v[206:209], v176 offset:54272
	ds_read_b128 v[210:213], v176 offset:55296
	ds_read_b128 v[214:217], v176 offset:56320
	global_load_lds_dwordx4 v[168:169], off
	s_add_i32 m0, s50, 0x2000
	s_add_u32 s48, s48, 0x40080
	v_lshl_add_u64 v[168:169], v[218:219], 0, s[16:17]
	s_addc_u32 s49, s49, 0
	s_add_i32 s50, s73, s55
	global_load_lds_dwordx4 v[168:169], off
	v_lshl_add_u64 v[168:169], s[48:49], 0, v[130:131]
	s_mov_b32 m0, s50
	s_nop 0
	global_load_lds_dwordx4 v[168:169], off
	v_lshl_add_u64 v[168:169], s[48:49], 0, v[134:135]
	s_add_i32 m0, s50, 0x2000
	s_nop 0
	global_load_lds_dwordx4 v[168:169], off
	v_lshl_add_u64 v[168:169], v[220:221], 0, s[16:17]
	s_mov_b32 m0, s61
	s_nop 0
	global_load_lds_dwordx4 v[168:169], off
	v_lshl_add_u64 v[168:169], v[222:223], 0, s[16:17]
	s_mov_b32 m0, s62
	s_nop 0
	global_load_lds_dwordx4 v[168:169], off
	s_waitcnt vmcnt(8)
	s_waitcnt lgkmcnt(0)
	s_barrier
	s_setprio 1
	v_mfma_f32_16x16x32_bf16 v[60:63], v[144:147], v[186:189], v[60:63]
	v_mfma_f32_16x16x32_bf16 v[56:59], v[152:155], v[186:189], v[56:59]
	v_mfma_f32_16x16x32_bf16 v[44:47], v[144:147], v[194:197], v[44:47]
	v_mfma_f32_16x16x32_bf16 v[40:43], v[152:155], v[194:197], v[40:43]
	v_mfma_f32_16x16x32_bf16 v[28:31], v[144:147], v[202:205], v[28:31]
	v_mfma_f32_16x16x32_bf16 v[24:27], v[152:155], v[202:205], v[24:27]
	v_mfma_f32_16x16x32_bf16 v[12:15], v[144:147], v[210:213], v[12:15]
	v_mfma_f32_16x16x32_bf16 v[8:11], v[152:155], v[210:213], v[8:11]
	v_mfma_f32_16x16x32_bf16 v[60:63], v[148:151], v[190:193], v[60:63]
	v_mfma_f32_16x16x32_bf16 v[56:59], v[156:159], v[190:193], v[56:59]
	v_mfma_f32_16x16x32_bf16 v[44:47], v[148:151], v[198:201], v[44:47]
	v_mfma_f32_16x16x32_bf16 v[40:43], v[156:159], v[198:201], v[40:43]
	v_mfma_f32_16x16x32_bf16 v[28:31], v[148:151], v[206:209], v[28:31]
	v_mfma_f32_16x16x32_bf16 v[24:27], v[156:159], v[206:209], v[24:27]
	v_mfma_f32_16x16x32_bf16 v[12:15], v[148:151], v[214:217], v[12:15]
	v_mfma_f32_16x16x32_bf16 v[8:11], v[156:159], v[214:217], v[8:11]
	s_setprio 0
	s_setprio 1
	v_mfma_f32_16x16x32_bf16 v[52:55], v[160:163], v[186:189], v[52:55]
	v_mfma_f32_16x16x32_bf16 v[48:51], v[178:181], v[186:189], v[48:51]
	v_mfma_f32_16x16x32_bf16 v[36:39], v[160:163], v[194:197], v[36:39]
	v_mfma_f32_16x16x32_bf16 v[32:35], v[178:181], v[194:197], v[32:35]
	v_mfma_f32_16x16x32_bf16 v[20:23], v[160:163], v[202:205], v[20:23]
	v_mfma_f32_16x16x32_bf16 v[16:19], v[178:181], v[202:205], v[16:19]
	v_mfma_f32_16x16x32_bf16 v[4:7], v[160:163], v[210:213], v[4:7]
	v_mfma_f32_16x16x32_bf16 v[0:3], v[178:181], v[210:213], v[0:3]
	v_mfma_f32_16x16x32_bf16 v[52:55], v[164:167], v[190:193], v[52:55]
	v_mfma_f32_16x16x32_bf16 v[48:51], v[182:185], v[190:193], v[48:51]
	v_mfma_f32_16x16x32_bf16 v[36:39], v[164:167], v[198:201], v[36:39]
	v_mfma_f32_16x16x32_bf16 v[32:35], v[182:185], v[198:201], v[32:35]
	v_mfma_f32_16x16x32_bf16 v[20:23], v[164:167], v[206:209], v[20:23]
	v_mfma_f32_16x16x32_bf16 v[16:19], v[182:185], v[206:209], v[16:19]
	v_mfma_f32_16x16x32_bf16 v[4:7], v[164:167], v[214:217], v[4:7]
	v_mfma_f32_16x16x32_bf16 v[0:3], v[182:185], v[214:217], v[0:3]
	s_setprio 0
	s_barrier
	s_add_i32 s71, s71, 2
	s_add_u32 s46, s46, 0x100
	s_addc_u32 s47, s47, 0
	s_add_u32 s41, s41, 0x100
	s_addc_u32 s70, s70, 0
	s_cmp_gt_u32 s71, 13
	s_cbranch_scc0 .LBB0_771
	s_and_b64 vcc, exec, s[18:19]
	s_cbranch_vccz .LBB0_774
	s_barrier

.LBB0_1033:
	ds_read_b128 v[144:147], v151
	ds_read_b128 v[162:165], v151 offset:1024
	ds_read_b128 v[166:169], v151 offset:2048
	ds_read_b128 v[172:175], v151 offset:3072
	ds_read_b128 v[176:179], v160
	ds_read_b128 v[180:183], v160 offset:1024
	ds_read_b128 v[184:187], v160 offset:2048
	ds_read_b128 v[188:191], v160 offset:3072
	s_add_u32 s42, s40, 0xfffc0080
	s_addc_u32 s43, s41, -1
	s_cmp_eq_u32 s65, 12
	s_cselect_b32 s45, s1, s43
	s_cselect_b32 s44, s35, s42
	s_cselect_b32 s43, s27, s64
	s_cselect_b32 s42, s62, s63
	v_lshl_add_u64 v[224:225], s[40:41], 0, v[136:137]
	s_add_i32 m0, s11, 0xc000
	ds_read_b128 v[192:195], v161
	ds_read_b128 v[196:199], v161 offset:1024
	ds_read_b128 v[200:203], v161 offset:2048
	ds_read_b128 v[204:207], v161 offset:3072
	ds_read_b128 v[208:211], v161 offset:4096
	ds_read_b128 v[212:215], v161 offset:5120
	ds_read_b128 v[216:219], v161 offset:6144
	ds_read_b128 v[220:223], v161 offset:7168
	global_load_lds_dwordx4 v[224:225], off
	v_lshl_add_u64 v[224:225], s[40:41], 0, v[138:139]
	s_add_i32 m0, s11, 0xe000
	s_nop 0
	global_load_lds_dwordx4 v[224:225], off
	s_waitcnt vmcnt(8)
	s_waitcnt lgkmcnt(0)
	s_barrier
	s_setprio 1
	v_mfma_f32_16x16x32_bf16 v[124:127], v[144:147], v[192:195], v[124:127]
	v_mfma_f32_16x16x32_bf16 v[120:123], v[166:169], v[192:195], v[120:123]
	v_mfma_f32_16x16x32_bf16 v[108:111], v[144:147], v[200:203], v[108:111]
	v_mfma_f32_16x16x32_bf16 v[104:107], v[166:169], v[200:203], v[104:107]
	v_mfma_f32_16x16x32_bf16 v[92:95], v[144:147], v[208:211], v[92:95]
	v_mfma_f32_16x16x32_bf16 v[88:91], v[166:169], v[208:211], v[88:91]
	v_mfma_f32_16x16x32_bf16 v[76:79], v[144:147], v[216:219], v[76:79]
	v_mfma_f32_16x16x32_bf16 v[72:75], v[166:169], v[216:219], v[72:75]
	v_mfma_f32_16x16x32_bf16 v[124:127], v[162:165], v[196:199], v[124:127]
	v_mfma_f32_16x16x32_bf16 v[120:123], v[172:175], v[196:199], v[120:123]
	v_mfma_f32_16x16x32_bf16 v[108:111], v[162:165], v[204:207], v[108:111]
	v_mfma_f32_16x16x32_bf16 v[104:107], v[172:175], v[204:207], v[104:107]
	v_mfma_f32_16x16x32_bf16 v[92:95], v[162:165], v[212:215], v[92:95]
	v_mfma_f32_16x16x32_bf16 v[88:91], v[172:175], v[212:215], v[88:91]
	v_mfma_f32_16x16x32_bf16 v[76:79], v[162:165], v[220:223], v[76:79]
	v_mfma_f32_16x16x32_bf16 v[72:75], v[172:175], v[220:223], v[72:75]
	s_setprio 0
	s_setprio 1
	v_mfma_f32_16x16x32_bf16 v[116:119], v[176:179], v[192:195], v[116:119]
	v_mfma_f32_16x16x32_bf16 v[112:115], v[184:187], v[192:195], v[112:115]
	v_mfma_f32_16x16x32_bf16 v[100:103], v[176:179], v[200:203], v[100:103]
	v_mfma_f32_16x16x32_bf16 v[96:99], v[184:187], v[200:203], v[96:99]
	v_mfma_f32_16x16x32_bf16 v[84:87], v[176:179], v[208:211], v[84:87]
	v_mfma_f32_16x16x32_bf16 v[80:83], v[184:187], v[208:211], v[80:83]
	v_mfma_f32_16x16x32_bf16 v[68:71], v[176:179], v[216:219], v[68:71]
	v_mfma_f32_16x16x32_bf16 v[64:67], v[184:187], v[216:219], v[64:67]
	v_mfma_f32_16x16x32_bf16 v[116:119], v[180:183], v[196:199], v[116:119]
	v_mfma_f32_16x16x32_bf16 v[112:115], v[188:191], v[196:199], v[112:115]
	v_mfma_f32_16x16x32_bf16 v[100:103], v[180:183], v[204:207], v[100:103]
	v_mfma_f32_16x16x32_bf16 v[96:99], v[188:191], v[204:207], v[96:99]
	v_mfma_f32_16x16x32_bf16 v[84:87], v[180:183], v[212:215], v[84:87]
	v_mfma_f32_16x16x32_bf16 v[80:83], v[188:191], v[212:215], v[80:83]
	v_mfma_f32_16x16x32_bf16 v[68:71], v[180:183], v[220:223], v[68:71]
	v_mfma_f32_16x16x32_bf16 v[64:67], v[188:191], v[220:223], v[64:67]
	s_setprio 0
	s_barrier
	s_add_i32 s66, s60, s47
	v_lshl_add_u64 v[224:225], s[42:43], 0, v[130:131]
	s_mov_b32 m0, s66
	ds_read_b128 v[192:195], v161 offset:16384
	ds_read_b128 v[196:199], v161 offset:17408
	ds_read_b128 v[200:203], v161 offset:18432
	ds_read_b128 v[204:207], v161 offset:19456
	ds_read_b128 v[208:211], v161 offset:20480
	ds_read_b128 v[212:215], v161 offset:21504
	ds_read_b128 v[216:219], v161 offset:22528
	ds_read_b128 v[220:223], v161 offset:23552
	global_load_lds_dwordx4 v[224:225], off
	s_add_i32 m0, s66, 0x2000
	s_add_u32 s66, s42, 0x40000
	v_lshl_add_u64 v[226:227], s[42:43], 0, v[134:135]
	s_addc_u32 s67, s43, 0
	s_add_i32 s68, s61, s47
	global_load_lds_dwordx4 v[226:227], off
	v_lshl_add_u64 v[228:229], s[66:67], 0, v[130:131]
	s_mov_b32 m0, s68
	v_lshl_add_u64 v[230:231], s[44:45], 0, v[132:133]
	global_load_lds_dwordx4 v[228:229], off
	v_lshl_add_u64 v[228:229], s[66:67], 0, v[134:135]
	s_add_i32 m0, s68, 0x2000
	s_nop 0
	global_load_lds_dwordx4 v[228:229], off
	v_lshl_add_u64 v[228:229], s[44:45], 0, v[128:129]
	s_mov_b32 m0, s11
	s_nop 0
	global_load_lds_dwordx4 v[228:229], off
	s_mov_b32 m0, s48
	s_nop 0
	global_load_lds_dwordx4 v[230:231], off
	s_waitcnt vmcnt(8)
	s_waitcnt lgkmcnt(0)
	s_barrier
	s_setprio 1
	v_mfma_f32_16x16x32_bf16 v[60:63], v[144:147], v[192:195], v[60:63]
	v_mfma_f32_16x16x32_bf16 v[56:59], v[166:169], v[192:195], v[56:59]
	v_mfma_f32_16x16x32_bf16 v[44:47], v[144:147], v[200:203], v[44:47]
	v_mfma_f32_16x16x32_bf16 v[40:43], v[166:169], v[200:203], v[40:43]
	v_mfma_f32_16x16x32_bf16 v[28:31], v[144:147], v[208:211], v[28:31]
	v_mfma_f32_16x16x32_bf16 v[24:27], v[166:169], v[208:211], v[24:27]
	v_mfma_f32_16x16x32_bf16 v[12:15], v[144:147], v[216:219], v[12:15]
	v_mfma_f32_16x16x32_bf16 v[8:11], v[166:169], v[216:219], v[8:11]
	v_mfma_f32_16x16x32_bf16 v[60:63], v[162:165], v[196:199], v[60:63]
	v_mfma_f32_16x16x32_bf16 v[56:59], v[172:175], v[196:199], v[56:59]
	v_mfma_f32_16x16x32_bf16 v[44:47], v[162:165], v[204:207], v[44:47]
	v_mfma_f32_16x16x32_bf16 v[40:43], v[172:175], v[204:207], v[40:43]
	v_mfma_f32_16x16x32_bf16 v[28:31], v[162:165], v[212:215], v[28:31]
	v_mfma_f32_16x16x32_bf16 v[24:27], v[172:175], v[212:215], v[24:27]
	v_mfma_f32_16x16x32_bf16 v[12:15], v[162:165], v[220:223], v[12:15]
	v_mfma_f32_16x16x32_bf16 v[8:11], v[172:175], v[220:223], v[8:11]
	s_setprio 0
	s_setprio 1
	v_mfma_f32_16x16x32_bf16 v[52:55], v[176:179], v[192:195], v[52:55]
	v_mfma_f32_16x16x32_bf16 v[48:51], v[184:187], v[192:195], v[48:51]
	v_mfma_f32_16x16x32_bf16 v[36:39], v[176:179], v[200:203], v[36:39]
	v_mfma_f32_16x16x32_bf16 v[32:35], v[184:187], v[200:203], v[32:35]
	v_mfma_f32_16x16x32_bf16 v[20:23], v[176:179], v[208:211], v[20:23]
	v_mfma_f32_16x16x32_bf16 v[16:19], v[184:187], v[208:211], v[16:19]
	v_mfma_f32_16x16x32_bf16 v[4:7], v[176:179], v[216:219], v[4:7]
	v_mfma_f32_16x16x32_bf16 v[0:3], v[184:187], v[216:219], v[0:3]
	v_mfma_f32_16x16x32_bf16 v[52:55], v[180:183], v[196:199], v[52:55]
	v_mfma_f32_16x16x32_bf16 v[48:51], v[188:191], v[196:199], v[48:51]
	v_mfma_f32_16x16x32_bf16 v[36:39], v[180:183], v[204:207], v[36:39]
	v_mfma_f32_16x16x32_bf16 v[32:35], v[188:191], v[204:207], v[32:35]
	v_mfma_f32_16x16x32_bf16 v[20:23], v[180:183], v[212:215], v[20:23]
	v_mfma_f32_16x16x32_bf16 v[16:19], v[188:191], v[212:215], v[16:19]
	v_mfma_f32_16x16x32_bf16 v[4:7], v[180:183], v[220:223], v[4:7]
	v_mfma_f32_16x16x32_bf16 v[0:3], v[188:191], v[220:223], v[0:3]
	s_setprio 0
	s_barrier
	s_add_i32 s66, 0, 0x18000
	v_add_u32_e32 v171, s66, v149
	s_add_i32 s67, 0, 0x1c000
	ds_read_b128 v[144:147], v171
	ds_read_b128 v[162:165], v171 offset:1024
	ds_read_b128 v[166:169], v171 offset:2048
	ds_read_b128 v[172:175], v171 offset:3072
	v_add_u32_e32 v171, s67, v149
	ds_read_b128 v[176:179], v171
	ds_read_b128 v[180:183], v171 offset:1024
	ds_read_b128 v[184:187], v171 offset:2048
	ds_read_b128 v[188:191], v171 offset:3072
	s_add_u32 s44, s44, 0x40000
	s_addc_u32 s45, s45, 0
	s_mov_b32 m0, s49
	v_lshl_add_u64 v[232:233], s[44:45], 0, v[128:129]
	ds_read_b128 v[192:195], v161 offset:32768
	ds_read_b128 v[196:199], v161 offset:33792
	ds_read_b128 v[200:203], v161 offset:34816
	ds_read_b128 v[204:207], v161 offset:35840
	ds_read_b128 v[208:211], v161 offset:36864
	ds_read_b128 v[212:215], v161 offset:37888
	ds_read_b128 v[216:219], v161 offset:38912
	ds_read_b128 v[220:223], v161 offset:39936
	global_load_lds_dwordx4 v[232:233], off
	v_lshl_add_u64 v[232:233], s[44:45], 0, v[132:133]
	s_mov_b32 m0, s51
	s_nop 0
	global_load_lds_dwordx4 v[232:233], off
	s_waitcnt vmcnt(8)
	s_waitcnt lgkmcnt(0)
	s_barrier
	s_setprio 1
	v_mfma_f32_16x16x32_bf16 v[124:127], v[144:147], v[192:195], v[124:127]
	v_mfma_f32_16x16x32_bf16 v[120:123], v[166:169], v[192:195], v[120:123]
	v_mfma_f32_16x16x32_bf16 v[108:111], v[144:147], v[200:203], v[108:111]
	v_mfma_f32_16x16x32_bf16 v[104:107], v[166:169], v[200:203], v[104:107]
	v_mfma_f32_16x16x32_bf16 v[92:95], v[144:147], v[208:211], v[92:95]
	v_mfma_f32_16x16x32_bf16 v[88:91], v[166:169], v[208:211], v[88:91]
	v_mfma_f32_16x16x32_bf16 v[76:79], v[144:147], v[216:219], v[76:79]
	v_mfma_f32_16x16x32_bf16 v[72:75], v[166:169], v[216:219], v[72:75]
	v_mfma_f32_16x16x32_bf16 v[124:127], v[162:165], v[196:199], v[124:127]
	v_mfma_f32_16x16x32_bf16 v[120:123], v[172:175], v[196:199], v[120:123]
	v_mfma_f32_16x16x32_bf16 v[108:111], v[162:165], v[204:207], v[108:111]
	v_mfma_f32_16x16x32_bf16 v[104:107], v[172:175], v[204:207], v[104:107]
	v_mfma_f32_16x16x32_bf16 v[92:95], v[162:165], v[212:215], v[92:95]
	v_mfma_f32_16x16x32_bf16 v[88:91], v[172:175], v[212:215], v[88:91]
	v_mfma_f32_16x16x32_bf16 v[76:79], v[162:165], v[220:223], v[76:79]
	v_mfma_f32_16x16x32_bf16 v[72:75], v[172:175], v[220:223], v[72:75]
	s_setprio 0
	s_setprio 1
	v_mfma_f32_16x16x32_bf16 v[116:119], v[176:179], v[192:195], v[116:119]
	v_mfma_f32_16x16x32_bf16 v[112:115], v[184:187], v[192:195], v[112:115]
	v_mfma_f32_16x16x32_bf16 v[100:103], v[176:179], v[200:203], v[100:103]
	v_mfma_f32_16x16x32_bf16 v[96:99], v[184:187], v[200:203], v[96:99]
	v_mfma_f32_16x16x32_bf16 v[84:87], v[176:179], v[208:211], v[84:87]
	v_mfma_f32_16x16x32_bf16 v[80:83], v[184:187], v[208:211], v[80:83]
	v_mfma_f32_16x16x32_bf16 v[68:71], v[176:179], v[216:219], v[68:71]
	v_mfma_f32_16x16x32_bf16 v[64:67], v[184:187], v[216:219], v[64:67]
	v_mfma_f32_16x16x32_bf16 v[116:119], v[180:183], v[196:199], v[116:119]
	v_mfma_f32_16x16x32_bf16 v[112:115], v[188:191], v[196:199], v[112:115]
	v_mfma_f32_16x16x32_bf16 v[100:103], v[180:183], v[204:207], v[100:103]
	v_mfma_f32_16x16x32_bf16 v[96:99], v[188:191], v[204:207], v[96:99]
	v_mfma_f32_16x16x32_bf16 v[84:87], v[180:183], v[212:215], v[84:87]
	v_mfma_f32_16x16x32_bf16 v[80:83], v[188:191], v[212:215], v[80:83]
	v_mfma_f32_16x16x32_bf16 v[68:71], v[180:183], v[220:223], v[68:71]
	v_mfma_f32_16x16x32_bf16 v[64:67], v[188:191], v[220:223], v[64:67]
	s_setprio 0
	s_barrier
	s_add_i32 s44, s66, s47
	v_lshl_add_u64 v[224:225], v[224:225], 0, s[14:15]
	s_mov_b32 m0, s44
	ds_read_b128 v[192:195], v161 offset:49152
	ds_read_b128 v[196:199], v161 offset:50176
	ds_read_b128 v[200:203], v161 offset:51200
	ds_read_b128 v[204:207], v161 offset:52224
	ds_read_b128 v[208:211], v161 offset:53248
	ds_read_b128 v[212:215], v161 offset:54272
	ds_read_b128 v[216:219], v161 offset:55296
	ds_read_b128 v[220:223], v161 offset:56320
	global_load_lds_dwordx4 v[224:225], off
	s_add_i32 m0, s44, 0x2000
	s_add_u32 s42, s42, 0x40080
	v_lshl_add_u64 v[224:225], v[226:227], 0, s[14:15]
	s_addc_u32 s43, s43, 0
	s_add_i32 s44, s67, s47
	global_load_lds_dwordx4 v[224:225], off
	v_lshl_add_u64 v[224:225], s[42:43], 0, v[130:131]
	s_mov_b32 m0, s44
	s_nop 0
	global_load_lds_dwordx4 v[224:225], off
	v_lshl_add_u64 v[224:225], s[42:43], 0, v[134:135]
	s_add_i32 m0, s44, 0x2000
	s_nop 0
	global_load_lds_dwordx4 v[224:225], off
	v_lshl_add_u64 v[224:225], v[228:229], 0, s[14:15]
	s_mov_b32 m0, s53
	s_nop 0
	global_load_lds_dwordx4 v[224:225], off
	v_lshl_add_u64 v[224:225], v[230:231], 0, s[14:15]
	s_mov_b32 m0, s54
	s_nop 0
	global_load_lds_dwordx4 v[224:225], off
	s_waitcnt vmcnt(8)
	s_waitcnt lgkmcnt(0)
	s_barrier
	s_setprio 1
	v_mfma_f32_16x16x32_bf16 v[60:63], v[144:147], v[192:195], v[60:63]
	v_mfma_f32_16x16x32_bf16 v[56:59], v[166:169], v[192:195], v[56:59]
	v_mfma_f32_16x16x32_bf16 v[44:47], v[144:147], v[200:203], v[44:47]
	v_mfma_f32_16x16x32_bf16 v[40:43], v[166:169], v[200:203], v[40:43]
	v_mfma_f32_16x16x32_bf16 v[28:31], v[144:147], v[208:211], v[28:31]
	v_mfma_f32_16x16x32_bf16 v[24:27], v[166:169], v[208:211], v[24:27]
	v_mfma_f32_16x16x32_bf16 v[12:15], v[144:147], v[216:219], v[12:15]
	v_mfma_f32_16x16x32_bf16 v[8:11], v[166:169], v[216:219], v[8:11]
	v_mfma_f32_16x16x32_bf16 v[60:63], v[162:165], v[196:199], v[60:63]
	v_mfma_f32_16x16x32_bf16 v[56:59], v[172:175], v[196:199], v[56:59]
	v_mfma_f32_16x16x32_bf16 v[44:47], v[162:165], v[204:207], v[44:47]
	v_mfma_f32_16x16x32_bf16 v[40:43], v[172:175], v[204:207], v[40:43]
	v_mfma_f32_16x16x32_bf16 v[28:31], v[162:165], v[212:215], v[28:31]
	v_mfma_f32_16x16x32_bf16 v[24:27], v[172:175], v[212:215], v[24:27]
	v_mfma_f32_16x16x32_bf16 v[12:15], v[162:165], v[220:223], v[12:15]
	v_mfma_f32_16x16x32_bf16 v[8:11], v[172:175], v[220:223], v[8:11]
	s_setprio 0
	s_setprio 1
	v_mfma_f32_16x16x32_bf16 v[52:55], v[176:179], v[192:195], v[52:55]
	v_mfma_f32_16x16x32_bf16 v[48:51], v[184:187], v[192:195], v[48:51]
	v_mfma_f32_16x16x32_bf16 v[36:39], v[176:179], v[200:203], v[36:39]
	v_mfma_f32_16x16x32_bf16 v[32:35], v[184:187], v[200:203], v[32:35]
	v_mfma_f32_16x16x32_bf16 v[20:23], v[176:179], v[208:211], v[20:23]
	v_mfma_f32_16x16x32_bf16 v[16:19], v[184:187], v[208:211], v[16:19]
	v_mfma_f32_16x16x32_bf16 v[4:7], v[176:179], v[216:219], v[4:7]
	v_mfma_f32_16x16x32_bf16 v[0:3], v[184:187], v[216:219], v[0:3]
	v_mfma_f32_16x16x32_bf16 v[52:55], v[180:183], v[196:199], v[52:55]
	v_mfma_f32_16x16x32_bf16 v[48:51], v[188:191], v[196:199], v[48:51]
	v_mfma_f32_16x16x32_bf16 v[36:39], v[180:183], v[204:207], v[36:39]
	v_mfma_f32_16x16x32_bf16 v[32:35], v[188:191], v[204:207], v[32:35]
	v_mfma_f32_16x16x32_bf16 v[20:23], v[180:183], v[212:215], v[20:23]
	v_mfma_f32_16x16x32_bf16 v[16:19], v[188:191], v[212:215], v[16:19]
	v_mfma_f32_16x16x32_bf16 v[4:7], v[180:183], v[220:223], v[4:7]
	v_mfma_f32_16x16x32_bf16 v[0:3], v[188:191], v[220:223], v[0:3]
	s_setprio 0
	s_barrier
	s_add_i32 s65, s65, 2
	s_add_u32 s40, s40, 0x100
	s_addc_u32 s41, s41, 0
	s_add_u32 s63, s63, 0x100
	s_addc_u32 s64, s64, 0
	s_cmp_gt_u32 s65, 13
	s_cbranch_scc0 .LBB0_1033
	s_and_b64 vcc, exec, s[16:17]
	s_cbranch_vccz .LBB0_1036
	s_barrier

.LBB0_1091:
	ds_read_b128 v[144:147], v151
	ds_read_b128 v[162:165], v151 offset:1024
	ds_read_b128 v[166:169], v151 offset:2048
	ds_read_b128 v[172:175], v151 offset:3072
	ds_read_b128 v[176:179], v160
	ds_read_b128 v[180:183], v160 offset:1024
	ds_read_b128 v[184:187], v160 offset:2048
	ds_read_b128 v[188:191], v160 offset:3072
	s_add_u32 s46, s44, 0xfffc0080
	s_addc_u32 s47, s45, -1
	s_cmp_eq_u32 s71, 12
	s_cselect_b32 s49, s1, s47
	s_cselect_b32 s48, s33, s46
	s_cselect_b32 s47, s37, s70
	s_cselect_b32 s46, s39, s69
	v_lshl_add_u64 v[224:225], s[44:45], 0, v[136:137]
	s_add_i32 m0, s21, 0xc000
	ds_read_b128 v[192:195], v161
	ds_read_b128 v[196:199], v161 offset:1024
	ds_read_b128 v[200:203], v161 offset:2048
	ds_read_b128 v[204:207], v161 offset:3072
	ds_read_b128 v[208:211], v161 offset:4096
	ds_read_b128 v[212:215], v161 offset:5120
	ds_read_b128 v[216:219], v161 offset:6144
	ds_read_b128 v[220:223], v161 offset:7168
	global_load_lds_dwordx4 v[224:225], off
	v_lshl_add_u64 v[224:225], s[44:45], 0, v[138:139]
	s_add_i32 m0, s21, 0xe000
	s_nop 0
	global_load_lds_dwordx4 v[224:225], off
	s_waitcnt vmcnt(8)
	s_waitcnt lgkmcnt(0)
	s_barrier
	s_setprio 1
	v_mfma_f32_16x16x32_bf16 v[124:127], v[144:147], v[192:195], v[124:127]
	v_mfma_f32_16x16x32_bf16 v[120:123], v[166:169], v[192:195], v[120:123]
	v_mfma_f32_16x16x32_bf16 v[108:111], v[144:147], v[200:203], v[108:111]
	v_mfma_f32_16x16x32_bf16 v[104:107], v[166:169], v[200:203], v[104:107]
	v_mfma_f32_16x16x32_bf16 v[92:95], v[144:147], v[208:211], v[92:95]
	v_mfma_f32_16x16x32_bf16 v[88:91], v[166:169], v[208:211], v[88:91]
	v_mfma_f32_16x16x32_bf16 v[76:79], v[144:147], v[216:219], v[76:79]
	v_mfma_f32_16x16x32_bf16 v[72:75], v[166:169], v[216:219], v[72:75]
	v_mfma_f32_16x16x32_bf16 v[124:127], v[162:165], v[196:199], v[124:127]
	v_mfma_f32_16x16x32_bf16 v[120:123], v[172:175], v[196:199], v[120:123]
	v_mfma_f32_16x16x32_bf16 v[108:111], v[162:165], v[204:207], v[108:111]
	v_mfma_f32_16x16x32_bf16 v[104:107], v[172:175], v[204:207], v[104:107]
	v_mfma_f32_16x16x32_bf16 v[92:95], v[162:165], v[212:215], v[92:95]
	v_mfma_f32_16x16x32_bf16 v[88:91], v[172:175], v[212:215], v[88:91]
	v_mfma_f32_16x16x32_bf16 v[76:79], v[162:165], v[220:223], v[76:79]
	v_mfma_f32_16x16x32_bf16 v[72:75], v[172:175], v[220:223], v[72:75]
	s_setprio 0
	s_setprio 1
	v_mfma_f32_16x16x32_bf16 v[116:119], v[176:179], v[192:195], v[116:119]
	v_mfma_f32_16x16x32_bf16 v[112:115], v[184:187], v[192:195], v[112:115]
	v_mfma_f32_16x16x32_bf16 v[100:103], v[176:179], v[200:203], v[100:103]
	v_mfma_f32_16x16x32_bf16 v[96:99], v[184:187], v[200:203], v[96:99]
	v_mfma_f32_16x16x32_bf16 v[84:87], v[176:179], v[208:211], v[84:87]
	v_mfma_f32_16x16x32_bf16 v[80:83], v[184:187], v[208:211], v[80:83]
	v_mfma_f32_16x16x32_bf16 v[68:71], v[176:179], v[216:219], v[68:71]
	v_mfma_f32_16x16x32_bf16 v[64:67], v[184:187], v[216:219], v[64:67]
	v_mfma_f32_16x16x32_bf16 v[116:119], v[180:183], v[196:199], v[116:119]
	v_mfma_f32_16x16x32_bf16 v[112:115], v[188:191], v[196:199], v[112:115]
	v_mfma_f32_16x16x32_bf16 v[100:103], v[180:183], v[204:207], v[100:103]
	v_mfma_f32_16x16x32_bf16 v[96:99], v[188:191], v[204:207], v[96:99]
	v_mfma_f32_16x16x32_bf16 v[84:87], v[180:183], v[212:215], v[84:87]
	v_mfma_f32_16x16x32_bf16 v[80:83], v[188:191], v[212:215], v[80:83]
	v_mfma_f32_16x16x32_bf16 v[68:71], v[180:183], v[220:223], v[68:71]
	v_mfma_f32_16x16x32_bf16 v[64:67], v[188:191], v[220:223], v[64:67]
	s_setprio 0
	s_barrier
	s_add_i32 s72, s67, s55
	v_lshl_add_u64 v[224:225], s[46:47], 0, v[130:131]
	s_mov_b32 m0, s72
	ds_read_b128 v[192:195], v161 offset:16384
	ds_read_b128 v[196:199], v161 offset:17408
	ds_read_b128 v[200:203], v161 offset:18432
	ds_read_b128 v[204:207], v161 offset:19456
	ds_read_b128 v[208:211], v161 offset:20480
	ds_read_b128 v[212:215], v161 offset:21504
	ds_read_b128 v[216:219], v161 offset:22528
	ds_read_b128 v[220:223], v161 offset:23552
	global_load_lds_dwordx4 v[224:225], off
	s_add_i32 m0, s72, 0x2000
	s_add_u32 s72, s46, 0x40000
	v_lshl_add_u64 v[226:227], s[46:47], 0, v[134:135]
	s_addc_u32 s73, s47, 0
	s_add_i32 s74, s68, s55
	global_load_lds_dwordx4 v[226:227], off
	v_lshl_add_u64 v[228:229], s[72:73], 0, v[130:131]
	s_mov_b32 m0, s74
	v_lshl_add_u64 v[230:231], s[48:49], 0, v[132:133]
	global_load_lds_dwordx4 v[228:229], off
	v_lshl_add_u64 v[228:229], s[72:73], 0, v[134:135]
	s_add_i32 m0, s74, 0x2000
	s_nop 0
	global_load_lds_dwordx4 v[228:229], off
	v_lshl_add_u64 v[228:229], s[48:49], 0, v[128:129]
	s_mov_b32 m0, s21
	s_nop 0
	global_load_lds_dwordx4 v[228:229], off
	s_mov_b32 m0, s56
	s_nop 0
	global_load_lds_dwordx4 v[230:231], off
	s_waitcnt vmcnt(8)
	s_waitcnt lgkmcnt(0)
	s_barrier
	s_setprio 1
	v_mfma_f32_16x16x32_bf16 v[60:63], v[144:147], v[192:195], v[60:63]
	v_mfma_f32_16x16x32_bf16 v[56:59], v[166:169], v[192:195], v[56:59]
	v_mfma_f32_16x16x32_bf16 v[44:47], v[144:147], v[200:203], v[44:47]
	v_mfma_f32_16x16x32_bf16 v[40:43], v[166:169], v[200:203], v[40:43]
	v_mfma_f32_16x16x32_bf16 v[28:31], v[144:147], v[208:211], v[28:31]
	v_mfma_f32_16x16x32_bf16 v[24:27], v[166:169], v[208:211], v[24:27]
	v_mfma_f32_16x16x32_bf16 v[12:15], v[144:147], v[216:219], v[12:15]
	v_mfma_f32_16x16x32_bf16 v[8:11], v[166:169], v[216:219], v[8:11]
	v_mfma_f32_16x16x32_bf16 v[60:63], v[162:165], v[196:199], v[60:63]
	v_mfma_f32_16x16x32_bf16 v[56:59], v[172:175], v[196:199], v[56:59]
	v_mfma_f32_16x16x32_bf16 v[44:47], v[162:165], v[204:207], v[44:47]
	v_mfma_f32_16x16x32_bf16 v[40:43], v[172:175], v[204:207], v[40:43]
	v_mfma_f32_16x16x32_bf16 v[28:31], v[162:165], v[212:215], v[28:31]
	v_mfma_f32_16x16x32_bf16 v[24:27], v[172:175], v[212:215], v[24:27]
	v_mfma_f32_16x16x32_bf16 v[12:15], v[162:165], v[220:223], v[12:15]
	v_mfma_f32_16x16x32_bf16 v[8:11], v[172:175], v[220:223], v[8:11]
	s_setprio 0
	s_setprio 1
	v_mfma_f32_16x16x32_bf16 v[52:55], v[176:179], v[192:195], v[52:55]
	v_mfma_f32_16x16x32_bf16 v[48:51], v[184:187], v[192:195], v[48:51]
	v_mfma_f32_16x16x32_bf16 v[36:39], v[176:179], v[200:203], v[36:39]
	v_mfma_f32_16x16x32_bf16 v[32:35], v[184:187], v[200:203], v[32:35]
	v_mfma_f32_16x16x32_bf16 v[20:23], v[176:179], v[208:211], v[20:23]
	v_mfma_f32_16x16x32_bf16 v[16:19], v[184:187], v[208:211], v[16:19]
	v_mfma_f32_16x16x32_bf16 v[4:7], v[176:179], v[216:219], v[4:7]
	v_mfma_f32_16x16x32_bf16 v[0:3], v[184:187], v[216:219], v[0:3]
	v_mfma_f32_16x16x32_bf16 v[52:55], v[180:183], v[196:199], v[52:55]
	v_mfma_f32_16x16x32_bf16 v[48:51], v[188:191], v[196:199], v[48:51]
	v_mfma_f32_16x16x32_bf16 v[36:39], v[180:183], v[204:207], v[36:39]
	v_mfma_f32_16x16x32_bf16 v[32:35], v[188:191], v[204:207], v[32:35]
	v_mfma_f32_16x16x32_bf16 v[20:23], v[180:183], v[212:215], v[20:23]
	v_mfma_f32_16x16x32_bf16 v[16:19], v[188:191], v[212:215], v[16:19]
	v_mfma_f32_16x16x32_bf16 v[4:7], v[180:183], v[220:223], v[4:7]
	v_mfma_f32_16x16x32_bf16 v[0:3], v[188:191], v[220:223], v[0:3]
	s_setprio 0
	s_barrier
	s_add_i32 s72, 0, 0x18000
	v_add_u32_e32 v171, s72, v149
	s_add_i32 s73, 0, 0x1c000
	ds_read_b128 v[144:147], v171
	ds_read_b128 v[162:165], v171 offset:1024
	ds_read_b128 v[166:169], v171 offset:2048
	ds_read_b128 v[172:175], v171 offset:3072
	v_add_u32_e32 v171, s73, v149
	ds_read_b128 v[176:179], v171
	ds_read_b128 v[180:183], v171 offset:1024
	ds_read_b128 v[184:187], v171 offset:2048
	ds_read_b128 v[188:191], v171 offset:3072
	s_add_u32 s48, s48, 0x40000
	s_addc_u32 s49, s49, 0
	s_mov_b32 m0, s57
	v_lshl_add_u64 v[232:233], s[48:49], 0, v[128:129]
	ds_read_b128 v[192:195], v161 offset:32768
	ds_read_b128 v[196:199], v161 offset:33792
	ds_read_b128 v[200:203], v161 offset:34816
	ds_read_b128 v[204:207], v161 offset:35840
	ds_read_b128 v[208:211], v161 offset:36864
	ds_read_b128 v[212:215], v161 offset:37888
	ds_read_b128 v[216:219], v161 offset:38912
	ds_read_b128 v[220:223], v161 offset:39936
	global_load_lds_dwordx4 v[232:233], off
	v_lshl_add_u64 v[232:233], s[48:49], 0, v[132:133]
	s_mov_b32 m0, s60
	s_nop 0
	global_load_lds_dwordx4 v[232:233], off
	s_waitcnt vmcnt(8)
	s_waitcnt lgkmcnt(0)
	s_barrier
	s_setprio 1
	v_mfma_f32_16x16x32_bf16 v[124:127], v[144:147], v[192:195], v[124:127]
	v_mfma_f32_16x16x32_bf16 v[120:123], v[166:169], v[192:195], v[120:123]
	v_mfma_f32_16x16x32_bf16 v[108:111], v[144:147], v[200:203], v[108:111]
	v_mfma_f32_16x16x32_bf16 v[104:107], v[166:169], v[200:203], v[104:107]
	v_mfma_f32_16x16x32_bf16 v[92:95], v[144:147], v[208:211], v[92:95]
	v_mfma_f32_16x16x32_bf16 v[88:91], v[166:169], v[208:211], v[88:91]
	v_mfma_f32_16x16x32_bf16 v[76:79], v[144:147], v[216:219], v[76:79]
	v_mfma_f32_16x16x32_bf16 v[72:75], v[166:169], v[216:219], v[72:75]
	v_mfma_f32_16x16x32_bf16 v[124:127], v[162:165], v[196:199], v[124:127]
	v_mfma_f32_16x16x32_bf16 v[120:123], v[172:175], v[196:199], v[120:123]
	v_mfma_f32_16x16x32_bf16 v[108:111], v[162:165], v[204:207], v[108:111]
	v_mfma_f32_16x16x32_bf16 v[104:107], v[172:175], v[204:207], v[104:107]
	v_mfma_f32_16x16x32_bf16 v[92:95], v[162:165], v[212:215], v[92:95]
	v_mfma_f32_16x16x32_bf16 v[88:91], v[172:175], v[212:215], v[88:91]
	v_mfma_f32_16x16x32_bf16 v[76:79], v[162:165], v[220:223], v[76:79]
	v_mfma_f32_16x16x32_bf16 v[72:75], v[172:175], v[220:223], v[72:75]
	s_setprio 0
	s_setprio 1
	v_mfma_f32_16x16x32_bf16 v[116:119], v[176:179], v[192:195], v[116:119]
	v_mfma_f32_16x16x32_bf16 v[112:115], v[184:187], v[192:195], v[112:115]
	v_mfma_f32_16x16x32_bf16 v[100:103], v[176:179], v[200:203], v[100:103]
	v_mfma_f32_16x16x32_bf16 v[96:99], v[184:187], v[200:203], v[96:99]
	v_mfma_f32_16x16x32_bf16 v[84:87], v[176:179], v[208:211], v[84:87]
	v_mfma_f32_16x16x32_bf16 v[80:83], v[184:187], v[208:211], v[80:83]
	v_mfma_f32_16x16x32_bf16 v[68:71], v[176:179], v[216:219], v[68:71]
	v_mfma_f32_16x16x32_bf16 v[64:67], v[184:187], v[216:219], v[64:67]
	v_mfma_f32_16x16x32_bf16 v[116:119], v[180:183], v[196:199], v[116:119]
	v_mfma_f32_16x16x32_bf16 v[112:115], v[188:191], v[196:199], v[112:115]
	v_mfma_f32_16x16x32_bf16 v[100:103], v[180:183], v[204:207], v[100:103]
	v_mfma_f32_16x16x32_bf16 v[96:99], v[188:191], v[204:207], v[96:99]
	v_mfma_f32_16x16x32_bf16 v[84:87], v[180:183], v[212:215], v[84:87]
	v_mfma_f32_16x16x32_bf16 v[80:83], v[188:191], v[212:215], v[80:83]
	v_mfma_f32_16x16x32_bf16 v[68:71], v[180:183], v[220:223], v[68:71]
	v_mfma_f32_16x16x32_bf16 v[64:67], v[188:191], v[220:223], v[64:67]
	s_setprio 0
	s_barrier
	s_add_i32 s48, s72, s55
	v_lshl_add_u64 v[224:225], v[224:225], 0, s[16:17]
	s_mov_b32 m0, s48
	ds_read_b128 v[192:195], v161 offset:49152
	ds_read_b128 v[196:199], v161 offset:50176
	ds_read_b128 v[200:203], v161 offset:51200
	ds_read_b128 v[204:207], v161 offset:52224
	ds_read_b128 v[208:211], v161 offset:53248
	ds_read_b128 v[212:215], v161 offset:54272
	ds_read_b128 v[216:219], v161 offset:55296
	ds_read_b128 v[220:223], v161 offset:56320
	global_load_lds_dwordx4 v[224:225], off
	s_add_i32 m0, s48, 0x2000
	s_add_u32 s46, s46, 0x40080
	v_lshl_add_u64 v[224:225], v[226:227], 0, s[16:17]
	s_addc_u32 s47, s47, 0
	s_add_i32 s48, s73, s55
	global_load_lds_dwordx4 v[224:225], off
	v_lshl_add_u64 v[224:225], s[46:47], 0, v[130:131]
	s_mov_b32 m0, s48
	s_nop 0
	global_load_lds_dwordx4 v[224:225], off
	v_lshl_add_u64 v[224:225], s[46:47], 0, v[134:135]
	s_add_i32 m0, s48, 0x2000
	s_nop 0
	global_load_lds_dwordx4 v[224:225], off
	v_lshl_add_u64 v[224:225], v[228:229], 0, s[16:17]
	s_mov_b32 m0, s62
	s_nop 0
	global_load_lds_dwordx4 v[224:225], off
	v_lshl_add_u64 v[224:225], v[230:231], 0, s[16:17]
	s_mov_b32 m0, s63
	s_nop 0
	global_load_lds_dwordx4 v[224:225], off
	s_waitcnt vmcnt(8)
	s_waitcnt lgkmcnt(0)
	s_barrier
	s_setprio 1
	v_mfma_f32_16x16x32_bf16 v[60:63], v[144:147], v[192:195], v[60:63]
	v_mfma_f32_16x16x32_bf16 v[56:59], v[166:169], v[192:195], v[56:59]
	v_mfma_f32_16x16x32_bf16 v[44:47], v[144:147], v[200:203], v[44:47]
	v_mfma_f32_16x16x32_bf16 v[40:43], v[166:169], v[200:203], v[40:43]
	v_mfma_f32_16x16x32_bf16 v[28:31], v[144:147], v[208:211], v[28:31]
	v_mfma_f32_16x16x32_bf16 v[24:27], v[166:169], v[208:211], v[24:27]
	v_mfma_f32_16x16x32_bf16 v[12:15], v[144:147], v[216:219], v[12:15]
	v_mfma_f32_16x16x32_bf16 v[8:11], v[166:169], v[216:219], v[8:11]
	v_mfma_f32_16x16x32_bf16 v[60:63], v[162:165], v[196:199], v[60:63]
	v_mfma_f32_16x16x32_bf16 v[56:59], v[172:175], v[196:199], v[56:59]
	v_mfma_f32_16x16x32_bf16 v[44:47], v[162:165], v[204:207], v[44:47]
	v_mfma_f32_16x16x32_bf16 v[40:43], v[172:175], v[204:207], v[40:43]
	v_mfma_f32_16x16x32_bf16 v[28:31], v[162:165], v[212:215], v[28:31]
	v_mfma_f32_16x16x32_bf16 v[24:27], v[172:175], v[212:215], v[24:27]
	v_mfma_f32_16x16x32_bf16 v[12:15], v[162:165], v[220:223], v[12:15]
	v_mfma_f32_16x16x32_bf16 v[8:11], v[172:175], v[220:223], v[8:11]
	s_setprio 0
	s_setprio 1
	v_mfma_f32_16x16x32_bf16 v[52:55], v[176:179], v[192:195], v[52:55]
	v_mfma_f32_16x16x32_bf16 v[48:51], v[184:187], v[192:195], v[48:51]
	v_mfma_f32_16x16x32_bf16 v[36:39], v[176:179], v[200:203], v[36:39]
	v_mfma_f32_16x16x32_bf16 v[32:35], v[184:187], v[200:203], v[32:35]
	v_mfma_f32_16x16x32_bf16 v[20:23], v[176:179], v[208:211], v[20:23]
	v_mfma_f32_16x16x32_bf16 v[16:19], v[184:187], v[208:211], v[16:19]
	v_mfma_f32_16x16x32_bf16 v[4:7], v[176:179], v[216:219], v[4:7]
	v_mfma_f32_16x16x32_bf16 v[0:3], v[184:187], v[216:219], v[0:3]
	v_mfma_f32_16x16x32_bf16 v[52:55], v[180:183], v[196:199], v[52:55]
	v_mfma_f32_16x16x32_bf16 v[48:51], v[188:191], v[196:199], v[48:51]
	v_mfma_f32_16x16x32_bf16 v[36:39], v[180:183], v[204:207], v[36:39]
	v_mfma_f32_16x16x32_bf16 v[32:35], v[188:191], v[204:207], v[32:35]
	v_mfma_f32_16x16x32_bf16 v[20:23], v[180:183], v[212:215], v[20:23]
	v_mfma_f32_16x16x32_bf16 v[16:19], v[188:191], v[212:215], v[16:19]
	v_mfma_f32_16x16x32_bf16 v[4:7], v[180:183], v[220:223], v[4:7]
	v_mfma_f32_16x16x32_bf16 v[0:3], v[188:191], v[220:223], v[0:3]
	s_setprio 0
	s_barrier
	s_add_i32 s71, s71, 2
	s_add_u32 s44, s44, 0x100
	s_addc_u32 s45, s45, 0
	s_add_u32 s69, s69, 0x100
	s_addc_u32 s70, s70, 0
	s_cmp_gt_u32 s71, 13
	s_cbranch_scc0 .LBB0_1091
	s_and_b64 vcc, exec, s[18:19]
	s_cbranch_vccz .LBB0_1094
	s_barrier

.LBB0_1183:
	ds_read_b128 v[148:151], v164
	ds_read_b128 v[172:175], v164 offset:1024
	ds_read_b128 v[176:179], v164 offset:2048
	ds_read_b128 v[180:183], v164 offset:3072
	ds_read_b128 v[184:187], v165
	ds_read_b128 v[188:191], v165 offset:1024
	ds_read_b128 v[192:195], v165 offset:2048
	ds_read_b128 v[196:199], v165 offset:3072
	s_add_u32 s54, s52, 0xfffc0080
	s_addc_u32 s55, s53, -1
	s_cmp_eq_u32 s77, 12
	s_cselect_b32 s57, s45, s55
	s_cselect_b32 s56, s73, s54
	s_cselect_b32 s55, s43, s76
	s_cselect_b32 s54, s74, s75
	v_lshl_add_u64 v[168:169], s[52:53], 0, v[140:141]
	s_add_i32 m0, s51, 0xc000
	ds_read_b128 v[200:203], v166
	ds_read_b128 v[204:207], v166 offset:1024
	ds_read_b128 v[208:211], v166 offset:2048
	ds_read_b128 v[212:215], v166 offset:3072
	ds_read_b128 v[216:219], v166 offset:4096
	ds_read_b128 v[220:223], v166 offset:5120
	ds_read_b128 v[224:227], v166 offset:6144
	ds_read_b128 v[228:231], v166 offset:7168
	global_load_lds_dwordx4 v[168:169], off
	v_lshl_add_u64 v[168:169], s[52:53], 0, v[142:143]
	s_add_i32 m0, s51, 0xe000
	s_nop 0
	global_load_lds_dwordx4 v[168:169], off
	s_waitcnt vmcnt(8)
	s_waitcnt lgkmcnt(0)
	s_barrier
	s_setprio 1
	v_mfma_f32_16x16x32_bf16 v[124:127], v[148:151], v[200:203], v[124:127]
	v_mfma_f32_16x16x32_bf16 v[120:123], v[176:179], v[200:203], v[120:123]
	v_mfma_f32_16x16x32_bf16 v[108:111], v[148:151], v[208:211], v[108:111]
	v_mfma_f32_16x16x32_bf16 v[104:107], v[176:179], v[208:211], v[104:107]
	v_mfma_f32_16x16x32_bf16 v[92:95], v[148:151], v[216:219], v[92:95]
	v_mfma_f32_16x16x32_bf16 v[88:91], v[176:179], v[216:219], v[88:91]
	v_mfma_f32_16x16x32_bf16 v[76:79], v[148:151], v[224:227], v[76:79]
	v_mfma_f32_16x16x32_bf16 v[72:75], v[176:179], v[224:227], v[72:75]
	v_mfma_f32_16x16x32_bf16 v[124:127], v[172:175], v[204:207], v[124:127]
	v_mfma_f32_16x16x32_bf16 v[120:123], v[180:183], v[204:207], v[120:123]
	v_mfma_f32_16x16x32_bf16 v[108:111], v[172:175], v[212:215], v[108:111]
	v_mfma_f32_16x16x32_bf16 v[104:107], v[180:183], v[212:215], v[104:107]
	v_mfma_f32_16x16x32_bf16 v[92:95], v[172:175], v[220:223], v[92:95]
	v_mfma_f32_16x16x32_bf16 v[88:91], v[180:183], v[220:223], v[88:91]
	v_mfma_f32_16x16x32_bf16 v[76:79], v[172:175], v[228:231], v[76:79]
	v_mfma_f32_16x16x32_bf16 v[72:75], v[180:183], v[228:231], v[72:75]
	s_setprio 0
	s_setprio 1
	v_mfma_f32_16x16x32_bf16 v[116:119], v[184:187], v[200:203], v[116:119]
	v_mfma_f32_16x16x32_bf16 v[112:115], v[192:195], v[200:203], v[112:115]
	v_mfma_f32_16x16x32_bf16 v[100:103], v[184:187], v[208:211], v[100:103]
	v_mfma_f32_16x16x32_bf16 v[96:99], v[192:195], v[208:211], v[96:99]
	v_mfma_f32_16x16x32_bf16 v[84:87], v[184:187], v[216:219], v[84:87]
	v_mfma_f32_16x16x32_bf16 v[80:83], v[192:195], v[216:219], v[80:83]
	v_mfma_f32_16x16x32_bf16 v[68:71], v[184:187], v[224:227], v[68:71]
	v_mfma_f32_16x16x32_bf16 v[64:67], v[192:195], v[224:227], v[64:67]
	v_mfma_f32_16x16x32_bf16 v[116:119], v[188:191], v[204:207], v[116:119]
	v_mfma_f32_16x16x32_bf16 v[112:115], v[196:199], v[204:207], v[112:115]
	v_mfma_f32_16x16x32_bf16 v[100:103], v[188:191], v[212:215], v[100:103]
	v_mfma_f32_16x16x32_bf16 v[96:99], v[196:199], v[212:215], v[96:99]
	v_mfma_f32_16x16x32_bf16 v[84:87], v[188:191], v[220:223], v[84:87]
	v_mfma_f32_16x16x32_bf16 v[80:83], v[196:199], v[220:223], v[80:83]
	v_mfma_f32_16x16x32_bf16 v[68:71], v[188:191], v[228:231], v[68:71]
	v_mfma_f32_16x16x32_bf16 v[64:67], v[196:199], v[228:231], v[64:67]
	s_setprio 0
	s_barrier
	s_add_i32 s78, s70, s61
	v_lshl_add_u64 v[168:169], s[54:55], 0, v[130:131]
	s_mov_b32 m0, s78
	ds_read_b128 v[200:203], v166 offset:16384
	ds_read_b128 v[204:207], v166 offset:17408
	ds_read_b128 v[208:211], v166 offset:18432
	ds_read_b128 v[212:215], v166 offset:19456
	ds_read_b128 v[216:219], v166 offset:20480
	ds_read_b128 v[220:223], v166 offset:21504
	ds_read_b128 v[224:227], v166 offset:22528
	ds_read_b128 v[228:231], v166 offset:23552
	global_load_lds_dwordx4 v[168:169], off
	s_add_i32 m0, s78, 0x2000
	s_add_u32 s78, s54, 0x40000
	v_lshl_add_u64 v[232:233], s[54:55], 0, v[134:135]
	s_addc_u32 s79, s55, 0
	s_add_i32 s80, s71, s61
	global_load_lds_dwordx4 v[232:233], off
	v_lshl_add_u64 v[234:235], s[78:79], 0, v[130:131]
	s_mov_b32 m0, s80
	v_lshl_add_u64 v[236:237], s[56:57], 0, v[132:133]
	global_load_lds_dwordx4 v[234:235], off
	v_lshl_add_u64 v[234:235], s[78:79], 0, v[134:135]
	s_add_i32 m0, s80, 0x2000
	s_nop 0
	global_load_lds_dwordx4 v[234:235], off
	v_lshl_add_u64 v[234:235], s[56:57], 0, v[128:129]
	s_mov_b32 m0, s51
	s_nop 0
	global_load_lds_dwordx4 v[234:235], off
	s_mov_b32 m0, s62
	s_nop 0
	global_load_lds_dwordx4 v[236:237], off
	s_waitcnt vmcnt(8)
	s_waitcnt lgkmcnt(0)
	s_barrier
	s_setprio 1
	v_mfma_f32_16x16x32_bf16 v[60:63], v[148:151], v[200:203], v[60:63]
	v_mfma_f32_16x16x32_bf16 v[56:59], v[176:179], v[200:203], v[56:59]
	v_mfma_f32_16x16x32_bf16 v[44:47], v[148:151], v[208:211], v[44:47]
	v_mfma_f32_16x16x32_bf16 v[40:43], v[176:179], v[208:211], v[40:43]
	v_mfma_f32_16x16x32_bf16 v[28:31], v[148:151], v[216:219], v[28:31]
	v_mfma_f32_16x16x32_bf16 v[24:27], v[176:179], v[216:219], v[24:27]
	v_mfma_f32_16x16x32_bf16 v[12:15], v[148:151], v[224:227], v[12:15]
	v_mfma_f32_16x16x32_bf16 v[8:11], v[176:179], v[224:227], v[8:11]
	v_mfma_f32_16x16x32_bf16 v[60:63], v[172:175], v[204:207], v[60:63]
	v_mfma_f32_16x16x32_bf16 v[56:59], v[180:183], v[204:207], v[56:59]
	v_mfma_f32_16x16x32_bf16 v[44:47], v[172:175], v[212:215], v[44:47]
	v_mfma_f32_16x16x32_bf16 v[40:43], v[180:183], v[212:215], v[40:43]
	v_mfma_f32_16x16x32_bf16 v[28:31], v[172:175], v[220:223], v[28:31]
	v_mfma_f32_16x16x32_bf16 v[24:27], v[180:183], v[220:223], v[24:27]
	v_mfma_f32_16x16x32_bf16 v[12:15], v[172:175], v[228:231], v[12:15]
	v_mfma_f32_16x16x32_bf16 v[8:11], v[180:183], v[228:231], v[8:11]
	s_setprio 0
	s_setprio 1
	v_mfma_f32_16x16x32_bf16 v[52:55], v[184:187], v[200:203], v[52:55]
	v_mfma_f32_16x16x32_bf16 v[48:51], v[192:195], v[200:203], v[48:51]
	v_mfma_f32_16x16x32_bf16 v[36:39], v[184:187], v[208:211], v[36:39]
	v_mfma_f32_16x16x32_bf16 v[32:35], v[192:195], v[208:211], v[32:35]
	v_mfma_f32_16x16x32_bf16 v[20:23], v[184:187], v[216:219], v[20:23]
	v_mfma_f32_16x16x32_bf16 v[16:19], v[192:195], v[216:219], v[16:19]
	v_mfma_f32_16x16x32_bf16 v[4:7], v[184:187], v[224:227], v[4:7]
	v_mfma_f32_16x16x32_bf16 v[0:3], v[192:195], v[224:227], v[0:3]
	v_mfma_f32_16x16x32_bf16 v[52:55], v[188:191], v[204:207], v[52:55]
	v_mfma_f32_16x16x32_bf16 v[48:51], v[196:199], v[204:207], v[48:51]
	v_mfma_f32_16x16x32_bf16 v[36:39], v[188:191], v[212:215], v[36:39]
	v_mfma_f32_16x16x32_bf16 v[32:35], v[196:199], v[212:215], v[32:35]
	v_mfma_f32_16x16x32_bf16 v[20:23], v[188:191], v[220:223], v[20:23]
	v_mfma_f32_16x16x32_bf16 v[16:19], v[196:199], v[220:223], v[16:19]
	v_mfma_f32_16x16x32_bf16 v[4:7], v[188:191], v[228:231], v[4:7]
	v_mfma_f32_16x16x32_bf16 v[0:3], v[196:199], v[228:231], v[0:3]
	s_setprio 0
	s_barrier
	s_add_i32 s78, 0, 0x18000
	v_add_u32_e32 v138, s78, v163
	s_add_i32 s79, 0, 0x1c000
	ds_read_b128 v[148:151], v138
	ds_read_b128 v[172:175], v138 offset:1024
	ds_read_b128 v[176:179], v138 offset:2048
	ds_read_b128 v[180:183], v138 offset:3072
	v_add_u32_e32 v138, s79, v163
	ds_read_b128 v[184:187], v138
	ds_read_b128 v[188:191], v138 offset:1024
	ds_read_b128 v[192:195], v138 offset:2048
	ds_read_b128 v[196:199], v138 offset:3072
	s_add_u32 s56, s56, 0x40000
	s_addc_u32 s57, s57, 0
	s_mov_b32 m0, s63
	v_lshl_add_u64 v[238:239], s[56:57], 0, v[128:129]
	ds_read_b128 v[200:203], v166 offset:32768
	ds_read_b128 v[204:207], v166 offset:33792
	ds_read_b128 v[208:211], v166 offset:34816
	ds_read_b128 v[212:215], v166 offset:35840
	ds_read_b128 v[216:219], v166 offset:36864
	ds_read_b128 v[220:223], v166 offset:37888
	ds_read_b128 v[224:227], v166 offset:38912
	ds_read_b128 v[228:231], v166 offset:39936
	global_load_lds_dwordx4 v[238:239], off
	v_lshl_add_u64 v[238:239], s[56:57], 0, v[132:133]
	s_mov_b32 m0, s64
	s_nop 0
	global_load_lds_dwordx4 v[238:239], off
	s_waitcnt vmcnt(8)
	s_waitcnt lgkmcnt(0)
	s_barrier
	s_setprio 1
	v_mfma_f32_16x16x32_bf16 v[124:127], v[148:151], v[200:203], v[124:127]
	v_mfma_f32_16x16x32_bf16 v[120:123], v[176:179], v[200:203], v[120:123]
	v_mfma_f32_16x16x32_bf16 v[108:111], v[148:151], v[208:211], v[108:111]
	v_mfma_f32_16x16x32_bf16 v[104:107], v[176:179], v[208:211], v[104:107]
	v_mfma_f32_16x16x32_bf16 v[92:95], v[148:151], v[216:219], v[92:95]
	v_mfma_f32_16x16x32_bf16 v[88:91], v[176:179], v[216:219], v[88:91]
	v_mfma_f32_16x16x32_bf16 v[76:79], v[148:151], v[224:227], v[76:79]
	v_mfma_f32_16x16x32_bf16 v[72:75], v[176:179], v[224:227], v[72:75]
	v_mfma_f32_16x16x32_bf16 v[124:127], v[172:175], v[204:207], v[124:127]
	v_mfma_f32_16x16x32_bf16 v[120:123], v[180:183], v[204:207], v[120:123]
	v_mfma_f32_16x16x32_bf16 v[108:111], v[172:175], v[212:215], v[108:111]
	v_mfma_f32_16x16x32_bf16 v[104:107], v[180:183], v[212:215], v[104:107]
	v_mfma_f32_16x16x32_bf16 v[92:95], v[172:175], v[220:223], v[92:95]
	v_mfma_f32_16x16x32_bf16 v[88:91], v[180:183], v[220:223], v[88:91]
	v_mfma_f32_16x16x32_bf16 v[76:79], v[172:175], v[228:231], v[76:79]
	v_mfma_f32_16x16x32_bf16 v[72:75], v[180:183], v[228:231], v[72:75]
	s_setprio 0
	s_setprio 1
	v_mfma_f32_16x16x32_bf16 v[116:119], v[184:187], v[200:203], v[116:119]
	v_mfma_f32_16x16x32_bf16 v[112:115], v[192:195], v[200:203], v[112:115]
	v_mfma_f32_16x16x32_bf16 v[100:103], v[184:187], v[208:211], v[100:103]
	v_mfma_f32_16x16x32_bf16 v[96:99], v[192:195], v[208:211], v[96:99]
	v_mfma_f32_16x16x32_bf16 v[84:87], v[184:187], v[216:219], v[84:87]
	v_mfma_f32_16x16x32_bf16 v[80:83], v[192:195], v[216:219], v[80:83]
	v_mfma_f32_16x16x32_bf16 v[68:71], v[184:187], v[224:227], v[68:71]
	v_mfma_f32_16x16x32_bf16 v[64:67], v[192:195], v[224:227], v[64:67]
	v_mfma_f32_16x16x32_bf16 v[116:119], v[188:191], v[204:207], v[116:119]
	v_mfma_f32_16x16x32_bf16 v[112:115], v[196:199], v[204:207], v[112:115]
	v_mfma_f32_16x16x32_bf16 v[100:103], v[188:191], v[212:215], v[100:103]
	v_mfma_f32_16x16x32_bf16 v[96:99], v[196:199], v[212:215], v[96:99]
	v_mfma_f32_16x16x32_bf16 v[84:87], v[188:191], v[220:223], v[84:87]
	v_mfma_f32_16x16x32_bf16 v[80:83], v[196:199], v[220:223], v[80:83]
	v_mfma_f32_16x16x32_bf16 v[68:71], v[188:191], v[228:231], v[68:71]
	v_mfma_f32_16x16x32_bf16 v[64:67], v[196:199], v[228:231], v[64:67]
	s_setprio 0
	s_barrier
	s_add_i32 s56, s78, s61
	v_lshl_add_u64 v[168:169], v[168:169], 0, s[18:19]
	s_mov_b32 m0, s56
	ds_read_b128 v[200:203], v166 offset:49152
	ds_read_b128 v[204:207], v166 offset:50176
	ds_read_b128 v[208:211], v166 offset:51200
	ds_read_b128 v[212:215], v166 offset:52224
	ds_read_b128 v[216:219], v166 offset:53248
	ds_read_b128 v[220:223], v166 offset:54272
	ds_read_b128 v[224:227], v166 offset:55296
	ds_read_b128 v[228:231], v166 offset:56320
	global_load_lds_dwordx4 v[168:169], off
	s_add_i32 m0, s56, 0x2000
	s_add_u32 s54, s54, 0x40080
	v_lshl_add_u64 v[168:169], v[232:233], 0, s[18:19]
	s_addc_u32 s55, s55, 0
	s_add_i32 s56, s79, s61
	global_load_lds_dwordx4 v[168:169], off
	v_lshl_add_u64 v[168:169], s[54:55], 0, v[130:131]
	s_mov_b32 m0, s56
	s_nop 0
	global_load_lds_dwordx4 v[168:169], off
	v_lshl_add_u64 v[168:169], s[54:55], 0, v[134:135]
	s_add_i32 m0, s56, 0x2000
	s_nop 0
	global_load_lds_dwordx4 v[168:169], off
	v_lshl_add_u64 v[168:169], v[234:235], 0, s[18:19]
	s_mov_b32 m0, s66
	s_nop 0
	global_load_lds_dwordx4 v[168:169], off
	v_lshl_add_u64 v[168:169], v[236:237], 0, s[18:19]
	s_mov_b32 m0, s67
	s_nop 0
	global_load_lds_dwordx4 v[168:169], off
	s_waitcnt vmcnt(8)
	s_waitcnt lgkmcnt(0)
	s_barrier
	s_setprio 1
	v_mfma_f32_16x16x32_bf16 v[60:63], v[148:151], v[200:203], v[60:63]
	v_mfma_f32_16x16x32_bf16 v[56:59], v[176:179], v[200:203], v[56:59]
	v_mfma_f32_16x16x32_bf16 v[44:47], v[148:151], v[208:211], v[44:47]
	v_mfma_f32_16x16x32_bf16 v[40:43], v[176:179], v[208:211], v[40:43]
	v_mfma_f32_16x16x32_bf16 v[28:31], v[148:151], v[216:219], v[28:31]
	v_mfma_f32_16x16x32_bf16 v[24:27], v[176:179], v[216:219], v[24:27]
	v_mfma_f32_16x16x32_bf16 v[12:15], v[148:151], v[224:227], v[12:15]
	v_mfma_f32_16x16x32_bf16 v[8:11], v[176:179], v[224:227], v[8:11]
	v_mfma_f32_16x16x32_bf16 v[60:63], v[172:175], v[204:207], v[60:63]
	v_mfma_f32_16x16x32_bf16 v[56:59], v[180:183], v[204:207], v[56:59]
	v_mfma_f32_16x16x32_bf16 v[44:47], v[172:175], v[212:215], v[44:47]
	v_mfma_f32_16x16x32_bf16 v[40:43], v[180:183], v[212:215], v[40:43]
	v_mfma_f32_16x16x32_bf16 v[28:31], v[172:175], v[220:223], v[28:31]
	v_mfma_f32_16x16x32_bf16 v[24:27], v[180:183], v[220:223], v[24:27]
	v_mfma_f32_16x16x32_bf16 v[12:15], v[172:175], v[228:231], v[12:15]
	v_mfma_f32_16x16x32_bf16 v[8:11], v[180:183], v[228:231], v[8:11]
	s_setprio 0
	s_setprio 1
	v_mfma_f32_16x16x32_bf16 v[52:55], v[184:187], v[200:203], v[52:55]
	v_mfma_f32_16x16x32_bf16 v[48:51], v[192:195], v[200:203], v[48:51]
	v_mfma_f32_16x16x32_bf16 v[36:39], v[184:187], v[208:211], v[36:39]
	v_mfma_f32_16x16x32_bf16 v[32:35], v[192:195], v[208:211], v[32:35]
	v_mfma_f32_16x16x32_bf16 v[20:23], v[184:187], v[216:219], v[20:23]
	v_mfma_f32_16x16x32_bf16 v[16:19], v[192:195], v[216:219], v[16:19]
	v_mfma_f32_16x16x32_bf16 v[4:7], v[184:187], v[224:227], v[4:7]
	v_mfma_f32_16x16x32_bf16 v[0:3], v[192:195], v[224:227], v[0:3]
	v_mfma_f32_16x16x32_bf16 v[52:55], v[188:191], v[204:207], v[52:55]
	v_mfma_f32_16x16x32_bf16 v[48:51], v[196:199], v[204:207], v[48:51]
	v_mfma_f32_16x16x32_bf16 v[36:39], v[188:191], v[212:215], v[36:39]
	v_mfma_f32_16x16x32_bf16 v[32:35], v[196:199], v[212:215], v[32:35]
	v_mfma_f32_16x16x32_bf16 v[20:23], v[188:191], v[220:223], v[20:23]
	v_mfma_f32_16x16x32_bf16 v[16:19], v[196:199], v[220:223], v[16:19]
	v_mfma_f32_16x16x32_bf16 v[4:7], v[188:191], v[228:231], v[4:7]
	v_mfma_f32_16x16x32_bf16 v[0:3], v[196:199], v[228:231], v[0:3]
	s_setprio 0
	s_barrier
	s_add_i32 s77, s77, 2
	s_add_u32 s52, s52, 0x100
	s_addc_u32 s53, s53, 0
	s_add_u32 s75, s75, 0x100
	s_addc_u32 s76, s76, 0
	s_cmp_gt_u32 s77, 13
	s_cbranch_scc0 .LBB0_1183
	s_and_b64 vcc, exec, s[20:21]
	s_cbranch_vccz .LBB0_1186
	s_barrier

.LBB0_1269:
	ds_read_b128 v[154:157], v150
	ds_read_b128 v[158:161], v150 offset:1024
	ds_read_b128 v[162:165], v150 offset:2048
	ds_read_b128 v[166:169], v150 offset:3072
	ds_read_b128 v[172:175], v151
	ds_read_b128 v[176:179], v151 offset:1024
	ds_read_b128 v[180:183], v151 offset:2048
	ds_read_b128 v[184:187], v151 offset:3072
	s_add_u32 s40, s38, 0xfffc0080
	s_addc_u32 s41, s39, -1
	s_cmp_eq_u32 s69, 12
	s_cselect_b32 s43, s25, s41
	s_cselect_b32 s42, s37, s40
	s_cselect_b32 s41, s23, s68
	s_cselect_b32 s40, s66, s67
	v_lshl_add_u64 v[220:221], s[38:39], 0, v[138:139]
	s_add_i32 m0, s47, 0xc000
	ds_read_b128 v[188:191], v152
	ds_read_b128 v[192:195], v152 offset:1024
	ds_read_b128 v[196:199], v152 offset:2048
	ds_read_b128 v[200:203], v152 offset:3072
	ds_read_b128 v[204:207], v152 offset:4096
	ds_read_b128 v[208:211], v152 offset:5120
	ds_read_b128 v[212:215], v152 offset:6144
	ds_read_b128 v[216:219], v152 offset:7168
	global_load_lds_dwordx4 v[220:221], off
	v_lshl_add_u64 v[220:221], s[38:39], 0, v[140:141]
	s_add_i32 m0, s47, 0xe000
	s_nop 0
	global_load_lds_dwordx4 v[220:221], off
	s_waitcnt vmcnt(8)
	s_waitcnt lgkmcnt(0)
	s_barrier
	s_setprio 1
	v_mfma_f32_16x16x32_bf16 v[124:127], v[154:157], v[188:191], v[124:127]
	v_mfma_f32_16x16x32_bf16 v[120:123], v[162:165], v[188:191], v[120:123]
	v_mfma_f32_16x16x32_bf16 v[116:119], v[154:157], v[196:199], v[116:119]
	v_mfma_f32_16x16x32_bf16 v[112:115], v[162:165], v[196:199], v[112:115]
	v_mfma_f32_16x16x32_bf16 v[108:111], v[154:157], v[204:207], v[108:111]
	v_mfma_f32_16x16x32_bf16 v[100:103], v[162:165], v[204:207], v[100:103]
	v_mfma_f32_16x16x32_bf16 v[76:79], v[154:157], v[212:215], v[76:79]
	v_mfma_f32_16x16x32_bf16 v[72:75], v[162:165], v[212:215], v[72:75]
	v_mfma_f32_16x16x32_bf16 v[124:127], v[158:161], v[192:195], v[124:127]
	v_mfma_f32_16x16x32_bf16 v[120:123], v[166:169], v[192:195], v[120:123]
	v_mfma_f32_16x16x32_bf16 v[116:119], v[158:161], v[200:203], v[116:119]
	v_mfma_f32_16x16x32_bf16 v[112:115], v[166:169], v[200:203], v[112:115]
	v_mfma_f32_16x16x32_bf16 v[108:111], v[158:161], v[208:211], v[108:111]
	v_mfma_f32_16x16x32_bf16 v[100:103], v[166:169], v[208:211], v[100:103]
	v_mfma_f32_16x16x32_bf16 v[76:79], v[158:161], v[216:219], v[76:79]
	v_mfma_f32_16x16x32_bf16 v[72:75], v[166:169], v[216:219], v[72:75]
	s_setprio 0
	s_setprio 1
	v_mfma_f32_16x16x32_bf16 v[104:107], v[172:175], v[188:191], v[104:107]
	v_mfma_f32_16x16x32_bf16 v[96:99], v[180:183], v[188:191], v[96:99]
	v_mfma_f32_16x16x32_bf16 v[92:95], v[172:175], v[196:199], v[92:95]
	v_mfma_f32_16x16x32_bf16 v[88:91], v[180:183], v[196:199], v[88:91]
	v_mfma_f32_16x16x32_bf16 v[84:87], v[172:175], v[204:207], v[84:87]
	v_mfma_f32_16x16x32_bf16 v[80:83], v[180:183], v[204:207], v[80:83]
	v_mfma_f32_16x16x32_bf16 v[68:71], v[172:175], v[212:215], v[68:71]
	v_mfma_f32_16x16x32_bf16 v[64:67], v[180:183], v[212:215], v[64:67]
	v_mfma_f32_16x16x32_bf16 v[104:107], v[176:179], v[192:195], v[104:107]
	v_mfma_f32_16x16x32_bf16 v[96:99], v[184:187], v[192:195], v[96:99]
	v_mfma_f32_16x16x32_bf16 v[92:95], v[176:179], v[200:203], v[92:95]
	v_mfma_f32_16x16x32_bf16 v[88:91], v[184:187], v[200:203], v[88:91]
	v_mfma_f32_16x16x32_bf16 v[84:87], v[176:179], v[208:211], v[84:87]
	v_mfma_f32_16x16x32_bf16 v[80:83], v[184:187], v[208:211], v[80:83]
	v_mfma_f32_16x16x32_bf16 v[68:71], v[176:179], v[216:219], v[68:71]
	v_mfma_f32_16x16x32_bf16 v[64:67], v[184:187], v[216:219], v[64:67]
	s_setprio 0
	s_barrier
	s_add_i32 s70, s56, s46
	v_lshl_add_u64 v[220:221], s[40:41], 0, v[130:131]
	s_mov_b32 m0, s70
	ds_read_b128 v[188:191], v152 offset:16384
	ds_read_b128 v[192:195], v152 offset:17408
	ds_read_b128 v[196:199], v152 offset:18432
	ds_read_b128 v[200:203], v152 offset:19456
	ds_read_b128 v[204:207], v152 offset:20480
	ds_read_b128 v[208:211], v152 offset:21504
	ds_read_b128 v[212:215], v152 offset:22528
	ds_read_b128 v[216:219], v152 offset:23552
	global_load_lds_dwordx4 v[220:221], off
	s_add_i32 m0, s70, 0x2000
	s_add_u32 s70, s40, 0x40000
	v_lshl_add_u64 v[222:223], s[40:41], 0, v[134:135]
	s_addc_u32 s71, s41, 0
	s_add_i32 s72, s57, s46
	global_load_lds_dwordx4 v[222:223], off
	v_lshl_add_u64 v[224:225], s[70:71], 0, v[130:131]
	s_mov_b32 m0, s72
	v_lshl_add_u64 v[226:227], s[42:43], 0, v[132:133]
	global_load_lds_dwordx4 v[224:225], off
	v_lshl_add_u64 v[224:225], s[70:71], 0, v[134:135]
	s_add_i32 m0, s72, 0x2000
	s_nop 0
	global_load_lds_dwordx4 v[224:225], off
	v_lshl_add_u64 v[224:225], s[42:43], 0, v[128:129]
	s_mov_b32 m0, s47
	s_nop 0
	global_load_lds_dwordx4 v[224:225], off
	s_mov_b32 m0, s48
	s_nop 0
	global_load_lds_dwordx4 v[226:227], off
	s_waitcnt vmcnt(8)
	s_waitcnt lgkmcnt(0)
	s_barrier
	s_setprio 1
	v_mfma_f32_16x16x32_bf16 v[60:63], v[154:157], v[188:191], v[60:63]
	v_mfma_f32_16x16x32_bf16 v[56:59], v[162:165], v[188:191], v[56:59]
	v_mfma_f32_16x16x32_bf16 v[52:55], v[154:157], v[196:199], v[52:55]
	v_mfma_f32_16x16x32_bf16 v[44:47], v[162:165], v[196:199], v[44:47]
	v_mfma_f32_16x16x32_bf16 v[36:39], v[154:157], v[204:207], v[36:39]
	v_mfma_f32_16x16x32_bf16 v[28:31], v[162:165], v[204:207], v[28:31]
	v_mfma_f32_16x16x32_bf16 v[20:23], v[154:157], v[212:215], v[20:23]
	v_mfma_f32_16x16x32_bf16 v[12:15], v[162:165], v[212:215], v[12:15]
	v_mfma_f32_16x16x32_bf16 v[60:63], v[158:161], v[192:195], v[60:63]
	v_mfma_f32_16x16x32_bf16 v[56:59], v[166:169], v[192:195], v[56:59]
	v_mfma_f32_16x16x32_bf16 v[52:55], v[158:161], v[200:203], v[52:55]
	v_mfma_f32_16x16x32_bf16 v[44:47], v[166:169], v[200:203], v[44:47]
	v_mfma_f32_16x16x32_bf16 v[36:39], v[158:161], v[208:211], v[36:39]
	v_mfma_f32_16x16x32_bf16 v[28:31], v[166:169], v[208:211], v[28:31]
	v_mfma_f32_16x16x32_bf16 v[20:23], v[158:161], v[216:219], v[20:23]
	v_mfma_f32_16x16x32_bf16 v[12:15], v[166:169], v[216:219], v[12:15]
	s_setprio 0
	s_setprio 1
	v_mfma_f32_16x16x32_bf16 v[48:51], v[172:175], v[188:191], v[48:51]
	v_mfma_f32_16x16x32_bf16 v[40:43], v[180:183], v[188:191], v[40:43]
	v_mfma_f32_16x16x32_bf16 v[32:35], v[172:175], v[196:199], v[32:35]
	v_mfma_f32_16x16x32_bf16 v[24:27], v[180:183], v[196:199], v[24:27]
	v_mfma_f32_16x16x32_bf16 v[16:19], v[172:175], v[204:207], v[16:19]
	v_mfma_f32_16x16x32_bf16 v[8:11], v[180:183], v[204:207], v[8:11]
	v_mfma_f32_16x16x32_bf16 v[4:7], v[172:175], v[212:215], v[4:7]
	v_mfma_f32_16x16x32_bf16 v[0:3], v[180:183], v[212:215], v[0:3]
	v_mfma_f32_16x16x32_bf16 v[48:51], v[176:179], v[192:195], v[48:51]
	v_mfma_f32_16x16x32_bf16 v[40:43], v[184:187], v[192:195], v[40:43]
	v_mfma_f32_16x16x32_bf16 v[32:35], v[176:179], v[200:203], v[32:35]
	v_mfma_f32_16x16x32_bf16 v[24:27], v[184:187], v[200:203], v[24:27]
	v_mfma_f32_16x16x32_bf16 v[16:19], v[176:179], v[208:211], v[16:19]
	v_mfma_f32_16x16x32_bf16 v[8:11], v[184:187], v[208:211], v[8:11]
	v_mfma_f32_16x16x32_bf16 v[4:7], v[176:179], v[216:219], v[4:7]
	v_mfma_f32_16x16x32_bf16 v[0:3], v[184:187], v[216:219], v[0:3]
	s_setprio 0
	s_barrier
	s_add_i32 s70, 0, 0x18000
	v_add_u32_e32 v136, s70, v148
	s_add_i32 s71, 0, 0x1c000
	ds_read_b128 v[154:157], v136
	ds_read_b128 v[158:161], v136 offset:1024
	ds_read_b128 v[162:165], v136 offset:2048
	ds_read_b128 v[166:169], v136 offset:3072
	v_add_u32_e32 v136, s71, v148
	ds_read_b128 v[172:175], v136
	ds_read_b128 v[176:179], v136 offset:1024
	ds_read_b128 v[180:183], v136 offset:2048
	ds_read_b128 v[184:187], v136 offset:3072
	s_add_u32 s42, s42, 0x40000
	s_addc_u32 s43, s43, 0
	s_mov_b32 m0, s49
	v_lshl_add_u64 v[228:229], s[42:43], 0, v[128:129]
	ds_read_b128 v[188:191], v152 offset:32768
	ds_read_b128 v[192:195], v152 offset:33792
	ds_read_b128 v[196:199], v152 offset:34816
	ds_read_b128 v[200:203], v152 offset:35840
	ds_read_b128 v[204:207], v152 offset:36864
	ds_read_b128 v[208:211], v152 offset:37888
	ds_read_b128 v[212:215], v152 offset:38912
	ds_read_b128 v[216:219], v152 offset:39936
	global_load_lds_dwordx4 v[228:229], off
	v_lshl_add_u64 v[228:229], s[42:43], 0, v[132:133]
	s_mov_b32 m0, s50
	s_nop 0
	global_load_lds_dwordx4 v[228:229], off
	s_waitcnt vmcnt(8)
	s_waitcnt lgkmcnt(0)
	s_barrier
	s_setprio 1
	v_mfma_f32_16x16x32_bf16 v[124:127], v[154:157], v[188:191], v[124:127]
	v_mfma_f32_16x16x32_bf16 v[120:123], v[162:165], v[188:191], v[120:123]
	v_mfma_f32_16x16x32_bf16 v[116:119], v[154:157], v[196:199], v[116:119]
	v_mfma_f32_16x16x32_bf16 v[112:115], v[162:165], v[196:199], v[112:115]
	v_mfma_f32_16x16x32_bf16 v[108:111], v[154:157], v[204:207], v[108:111]
	v_mfma_f32_16x16x32_bf16 v[100:103], v[162:165], v[204:207], v[100:103]
	v_mfma_f32_16x16x32_bf16 v[76:79], v[154:157], v[212:215], v[76:79]
	v_mfma_f32_16x16x32_bf16 v[72:75], v[162:165], v[212:215], v[72:75]
	v_mfma_f32_16x16x32_bf16 v[124:127], v[158:161], v[192:195], v[124:127]
	v_mfma_f32_16x16x32_bf16 v[120:123], v[166:169], v[192:195], v[120:123]
	v_mfma_f32_16x16x32_bf16 v[116:119], v[158:161], v[200:203], v[116:119]
	v_mfma_f32_16x16x32_bf16 v[112:115], v[166:169], v[200:203], v[112:115]
	v_mfma_f32_16x16x32_bf16 v[108:111], v[158:161], v[208:211], v[108:111]
	v_mfma_f32_16x16x32_bf16 v[100:103], v[166:169], v[208:211], v[100:103]
	v_mfma_f32_16x16x32_bf16 v[76:79], v[158:161], v[216:219], v[76:79]
	v_mfma_f32_16x16x32_bf16 v[72:75], v[166:169], v[216:219], v[72:75]
	s_setprio 0
	s_setprio 1
	v_mfma_f32_16x16x32_bf16 v[104:107], v[172:175], v[188:191], v[104:107]
	v_mfma_f32_16x16x32_bf16 v[96:99], v[180:183], v[188:191], v[96:99]
	v_mfma_f32_16x16x32_bf16 v[92:95], v[172:175], v[196:199], v[92:95]
	v_mfma_f32_16x16x32_bf16 v[88:91], v[180:183], v[196:199], v[88:91]
	v_mfma_f32_16x16x32_bf16 v[84:87], v[172:175], v[204:207], v[84:87]
	v_mfma_f32_16x16x32_bf16 v[80:83], v[180:183], v[204:207], v[80:83]
	v_mfma_f32_16x16x32_bf16 v[68:71], v[172:175], v[212:215], v[68:71]
	v_mfma_f32_16x16x32_bf16 v[64:67], v[180:183], v[212:215], v[64:67]
	v_mfma_f32_16x16x32_bf16 v[104:107], v[176:179], v[192:195], v[104:107]
	v_mfma_f32_16x16x32_bf16 v[96:99], v[184:187], v[192:195], v[96:99]
	v_mfma_f32_16x16x32_bf16 v[92:95], v[176:179], v[200:203], v[92:95]
	v_mfma_f32_16x16x32_bf16 v[88:91], v[184:187], v[200:203], v[88:91]
	v_mfma_f32_16x16x32_bf16 v[84:87], v[176:179], v[208:211], v[84:87]
	v_mfma_f32_16x16x32_bf16 v[80:83], v[184:187], v[208:211], v[80:83]
	v_mfma_f32_16x16x32_bf16 v[68:71], v[176:179], v[216:219], v[68:71]
	v_mfma_f32_16x16x32_bf16 v[64:67], v[184:187], v[216:219], v[64:67]
	s_setprio 0
	s_barrier
	s_add_i32 s42, s70, s46
	v_lshl_add_u64 v[220:221], v[220:221], 0, s[12:13]
	s_mov_b32 m0, s42
	ds_read_b128 v[188:191], v152 offset:49152
	ds_read_b128 v[192:195], v152 offset:50176
	ds_read_b128 v[196:199], v152 offset:51200
	ds_read_b128 v[200:203], v152 offset:52224
	ds_read_b128 v[204:207], v152 offset:53248
	ds_read_b128 v[208:211], v152 offset:54272
	ds_read_b128 v[212:215], v152 offset:55296
	ds_read_b128 v[216:219], v152 offset:56320
	global_load_lds_dwordx4 v[220:221], off
	s_add_i32 m0, s42, 0x2000
	s_add_u32 s40, s40, 0x40080
	v_lshl_add_u64 v[220:221], v[222:223], 0, s[12:13]
	s_addc_u32 s41, s41, 0
	s_add_i32 s42, s71, s46
	global_load_lds_dwordx4 v[220:221], off
	v_lshl_add_u64 v[220:221], s[40:41], 0, v[130:131]
	s_mov_b32 m0, s42
	s_nop 0
	global_load_lds_dwordx4 v[220:221], off
	v_lshl_add_u64 v[220:221], s[40:41], 0, v[134:135]
	s_add_i32 m0, s42, 0x2000
	s_nop 0
	global_load_lds_dwordx4 v[220:221], off
	v_lshl_add_u64 v[220:221], v[224:225], 0, s[12:13]
	s_mov_b32 m0, s52
	s_nop 0
	global_load_lds_dwordx4 v[220:221], off
	v_lshl_add_u64 v[220:221], v[226:227], 0, s[12:13]
	s_mov_b32 m0, s53
	s_nop 0
	global_load_lds_dwordx4 v[220:221], off
	s_waitcnt vmcnt(8)
	s_waitcnt lgkmcnt(0)
	s_barrier
	s_setprio 1
	v_mfma_f32_16x16x32_bf16 v[60:63], v[154:157], v[188:191], v[60:63]
	v_mfma_f32_16x16x32_bf16 v[56:59], v[162:165], v[188:191], v[56:59]
	v_mfma_f32_16x16x32_bf16 v[52:55], v[154:157], v[196:199], v[52:55]
	v_mfma_f32_16x16x32_bf16 v[44:47], v[162:165], v[196:199], v[44:47]
	v_mfma_f32_16x16x32_bf16 v[36:39], v[154:157], v[204:207], v[36:39]
	v_mfma_f32_16x16x32_bf16 v[28:31], v[162:165], v[204:207], v[28:31]
	v_mfma_f32_16x16x32_bf16 v[20:23], v[154:157], v[212:215], v[20:23]
	v_mfma_f32_16x16x32_bf16 v[12:15], v[162:165], v[212:215], v[12:15]
	v_mfma_f32_16x16x32_bf16 v[60:63], v[158:161], v[192:195], v[60:63]
	v_mfma_f32_16x16x32_bf16 v[56:59], v[166:169], v[192:195], v[56:59]
	v_mfma_f32_16x16x32_bf16 v[52:55], v[158:161], v[200:203], v[52:55]
	v_mfma_f32_16x16x32_bf16 v[44:47], v[166:169], v[200:203], v[44:47]
	v_mfma_f32_16x16x32_bf16 v[36:39], v[158:161], v[208:211], v[36:39]
	v_mfma_f32_16x16x32_bf16 v[28:31], v[166:169], v[208:211], v[28:31]
	v_mfma_f32_16x16x32_bf16 v[20:23], v[158:161], v[216:219], v[20:23]
	v_mfma_f32_16x16x32_bf16 v[12:15], v[166:169], v[216:219], v[12:15]
	s_setprio 0
	s_setprio 1
	v_mfma_f32_16x16x32_bf16 v[48:51], v[172:175], v[188:191], v[48:51]
	v_mfma_f32_16x16x32_bf16 v[40:43], v[180:183], v[188:191], v[40:43]
	v_mfma_f32_16x16x32_bf16 v[32:35], v[172:175], v[196:199], v[32:35]
	v_mfma_f32_16x16x32_bf16 v[24:27], v[180:183], v[196:199], v[24:27]
	v_mfma_f32_16x16x32_bf16 v[16:19], v[172:175], v[204:207], v[16:19]
	v_mfma_f32_16x16x32_bf16 v[8:11], v[180:183], v[204:207], v[8:11]
	v_mfma_f32_16x16x32_bf16 v[4:7], v[172:175], v[212:215], v[4:7]
	v_mfma_f32_16x16x32_bf16 v[0:3], v[180:183], v[212:215], v[0:3]
	v_mfma_f32_16x16x32_bf16 v[48:51], v[176:179], v[192:195], v[48:51]
	v_mfma_f32_16x16x32_bf16 v[40:43], v[184:187], v[192:195], v[40:43]
	v_mfma_f32_16x16x32_bf16 v[32:35], v[176:179], v[200:203], v[32:35]
	v_mfma_f32_16x16x32_bf16 v[24:27], v[184:187], v[200:203], v[24:27]
	v_mfma_f32_16x16x32_bf16 v[16:19], v[176:179], v[208:211], v[16:19]
	v_mfma_f32_16x16x32_bf16 v[8:11], v[184:187], v[208:211], v[8:11]
	v_mfma_f32_16x16x32_bf16 v[4:7], v[176:179], v[216:219], v[4:7]
	v_mfma_f32_16x16x32_bf16 v[0:3], v[184:187], v[216:219], v[0:3]
	s_setprio 0
	s_barrier
	s_add_i32 s69, s69, 2
	s_add_u32 s38, s38, 0x100
	s_addc_u32 s39, s39, 0
	s_add_u32 s67, s67, 0x100
	s_addc_u32 s68, s68, 0
	s_cmp_gt_u32 s69, 13
	s_cbranch_scc0 .LBB0_1269
	s_and_b64 vcc, exec, s[14:15]
	s_cbranch_vccz .LBB0_1272
	s_barrier
